# phase1-single-pass-over-x-lds-row-reduction
# speedup vs baseline: 1.0137x; 1.0137x over previous
; #define LAS __attribute__((address_space(3)))
; template <int W>
; __device__ __forceinline__ void pool_chunk(const float* x, bf16_t* P, const LAS float* rs  , const f32x4 gs, const f32x4 sh, size_t r0, bool has_halo, int tid) {
;     f32x4 ring[W];
; #pragma unroll
;     for (int j = 0; j < W; ++j) ring[j] = (f32x4){0.f, 0.f, 0.f, 0.f};
;     f32x4 s = (f32x4){0.f, 0.f, 0.f, 0.f};
;     const float* xp = x + r0 * D + tid * 4;
;     if (has_halo) {
; #pragma unroll
;         for (int j = 0; j < W - 1; ++j) { const int t = -(W - 1) + j; const f32x4 h = *(const f32x4*)(xp + (long)t * D) * rs[t + 15] * gs + sh; ring[j] = h; s += h; }
;     }
; __device__ void phase1(const Params& p, LAS unsigned char* lds) {
;     LAS float* rs = (LAS float*)lds;
;     const int tid = threadIdx.x, wave = tid >> 6, lane = tid & 63;
;     const float* mod = (const float*)(p.ws + WS_MOD);
;     bf16_t* P = (bf16_t*)(p.ws + WS_H);
;     for (int it = blockIdx.x; it < M / 128; it += gridDim.x) {
;         const size_t r0 = (size_t)it * 128; const int b = (int)(r0 / SEQ); const bool has_halo = (r0 % SEQ) != 0;
;         for (int t = (has_halo ? -15 : 0) + wave; t < 128; t += 8) {
;             const float* xr = p.x + (r0 + t) * D + lane * 4; float ss = 0.f;
; #pragma unroll
;             for (int i = 0; i < 8; ++i) { const f32x4 v = *(const f32x4*)(xr + i * 256); ss += v[0] * v[0] + v[1] * v[1] + v[2] * v[2] + v[3] * v[3]; }
;             ss = wave_sum(ss);
;             if (lane == 0) rs[t + 15] = 1.0f / sqrtf(ss * (1.0f / D) + EPS);
;         }
;         __syncthreads();
;         const f32x4 g4 = *(const f32x4*)(p.n1g + tid * 4);
;         const f32x4 sc = *(const f32x4*)(mod + (size_t)b * MODW + 1 * D + tid * 4), sh = *(const f32x4*)(mod + (size_t)b * MODW + 0 * D + tid * 4);
;         const f32x4 gs = g4 * (sc + 1.0f);
;         const int grp = tid >> 7;
.LBB0_134:
	s_mov_b32 s0, 0
	s_andn2_b64 vcc, exec, s[14:15]
	s_cbranch_vccnz .LBB0_223
	v_readlane_b32 s4, v255, 3
	v_readlane_b32 s5, v255, 4
	v_lshlrev_b32_e32 v12, 4, v235
	v_readfirstlane_b32 s69, v235
	s_nop 3
	s_load_dwordx2 s[6:7], s[4:5], 0x0
	s_load_dwordx2 s[8:9], s[4:5], 0x20
	s_load_dwordx2 s[12:13], s[4:5], 0x90
	s_lshr_b32 s16, s2, 7
	s_and_b32 s18, s2, 0x7f
	s_lshr_b32 s69, s69, 7
	v_add_u32_e32 v13, 0x2000, v12
	s_waitcnt lgkmcnt(0)
	s_mul_i32 s19, s16, 0xc000
	s_add_u32 s20, s12, 0xa600000
	s_addc_u32 s21, s13, 0
	s_add_u32 s20, s20, s19
	s_addc_u32 s21, s21, 0
	global_load_dwordx4 v[16:19], v12, s[20:21]
	global_load_dwordx4 v[20:23], v13, s[20:21]
	global_load_dwordx4 v[24:27], v12, s[8:9]
	s_lshl_b32 s19, s2, 20
	s_add_u32 s30, s6, s19
	s_addc_u32 s31, s7, 0
	s_lshl_b32 s19, s2, 19
	s_add_u32 s36, s12, 0xa630000
	s_addc_u32 s37, s13, 0
	s_add_u32 s36, s36, s19
	s_addc_u32 s37, s37, 0
	s_mov_b32 s40, 8
	s_mov_b64 s[38:39], -1
	s_mov_b32 s41, 1
	s_cmp_eq_u32 s18, 0
	s_cbranch_scc1 .Lp1_nohalo
	s_mov_b32 s40, 9
	s_mov_b64 s[38:39], 0
	s_mov_b32 s41, 0
	s_sub_u32 s30, s30, 0x20000
	s_subb_u32 s31, s31, 0
.Lp1_nohalo:
	v_mov_b32_e32 v28, v12
	v_add_u32_e32 v29, 0x2000, v12
	v_add_u32_e32 v30, 0x4000, v12
	v_add_u32_e32 v31, 0x6000, v12
	v_add_u32_e32 v32, 0x8000, v12
	v_add_u32_e32 v33, 0xa000, v12
	v_add_u32_e32 v34, 0xc000, v12
	v_add_u32_e32 v35, 0xe000, v12
	v_add_u32_e32 v36, 0x10000, v12
	v_add_u32_e32 v37, 0x12000, v12
	v_add_u32_e32 v38, 0x14000, v12
	v_add_u32_e32 v39, 0x16000, v12
	v_add_u32_e32 v40, 0x18000, v12
	v_add_u32_e32 v41, 0x1a000, v12
	v_add_u32_e32 v42, 0x1c000, v12
	v_add_u32_e32 v43, 0x1e000, v12
	v_and_b32_e32 v44, -16, v235
	v_and_b32_e32 v45, 8, v235
	v_and_b32_e32 v46, 7, v235
	v_lshlrev_b32_e32 v44, 10, v44
	v_lshlrev_b32_e32 v45, 7, v45
	v_lshlrev_b32_e32 v46, 3, v46
	v_or3_b32 v44, v44, v45, v46
	v_xor_b32_e32 v45, 32, v44
	v_lshlrev_b32_e32 v46, 2, v235
	v_and_b32_e32 v47, 63, v235
	v_xor_b32_e32 v48, 32, v47
	v_lshlrev_b32_e32 v48, 2, v48
	v_xor_b32_e32 v49, 16, v47
	v_lshlrev_b32_e32 v49, 2, v49
	v_xor_b32_e32 v50, 8, v47
	v_lshlrev_b32_e32 v50, 2, v50
	v_xor_b32_e32 v51, 4, v47
	v_lshlrev_b32_e32 v51, 2, v51
	v_xor_b32_e32 v52, 2, v47
	v_lshlrev_b32_e32 v52, 2, v52
	v_xor_b32_e32 v53, 1, v47
	v_lshlrev_b32_e32 v53, 2, v53
	v_lshrrev_b32_e32 v57, 6, v235
	v_lshlrev_b32_e32 v58, 3, v57
	v_add_u32_e32 v58, 0x8000, v58
	v_lshlrev_b32_e32 v57, 12, v57
	v_lshl_add_u32 v47, v47, 2, v57
	v_mov_b32_e32 v59, 0x8000
	v_mov_b32_e32 v54, 0x358637bd
	v_mov_b32_e32 v55, 0x260
	s_mov_b32 s54, 0xf800000
	v_mov_b32_e32 v156, 0
	v_mov_b32_e32 v157, 0
	v_mov_b32_e32 v158, 0
	v_mov_b32_e32 v159, 0
	v_mov_b32_e32 v160, 0
	v_mov_b32_e32 v161, 0
	v_mov_b32_e32 v162, 0
	v_mov_b32_e32 v163, 0
	v_mov_b32_e32 v164, 0
	v_mov_b32_e32 v165, 0
	v_mov_b32_e32 v166, 0
	v_mov_b32_e32 v167, 0
	v_mov_b32_e32 v168, 0
	v_mov_b32_e32 v169, 0
	v_mov_b32_e32 v170, 0
	v_mov_b32_e32 v171, 0
	v_mov_b32_e32 v172, 0
	v_mov_b32_e32 v173, 0
	v_mov_b32_e32 v174, 0
	v_mov_b32_e32 v175, 0
	v_mov_b32_e32 v176, 0
	v_mov_b32_e32 v177, 0
	v_mov_b32_e32 v178, 0
	v_mov_b32_e32 v179, 0
	v_mov_b32_e32 v180, 0
	v_mov_b32_e32 v181, 0
	v_mov_b32_e32 v182, 0
	v_mov_b32_e32 v183, 0
	v_mov_b32_e32 v184, 0
	v_mov_b32_e32 v185, 0
	v_mov_b32_e32 v186, 0
	v_mov_b32_e32 v187, 0
	v_mov_b32_e32 v188, 0
	v_mov_b32_e32 v189, 0
	v_mov_b32_e32 v190, 0
	v_mov_b32_e32 v191, 0
	v_mov_b32_e32 v192, 0
	v_mov_b32_e32 v193, 0
	v_mov_b32_e32 v194, 0
	v_mov_b32_e32 v195, 0
	v_mov_b32_e32 v196, 0
	v_mov_b32_e32 v197, 0
	v_mov_b32_e32 v198, 0
	v_mov_b32_e32 v199, 0
	v_mov_b32_e32 v200, 0
	v_mov_b32_e32 v201, 0
	v_mov_b32_e32 v202, 0
	v_mov_b32_e32 v203, 0
	v_mov_b32_e32 v204, 0
	v_mov_b32_e32 v205, 0
	v_mov_b32_e32 v206, 0
	v_mov_b32_e32 v207, 0
	v_mov_b32_e32 v208, 0
	v_mov_b32_e32 v209, 0
	v_mov_b32_e32 v210, 0
	v_mov_b32_e32 v211, 0
	v_mov_b32_e32 v212, 0
	v_mov_b32_e32 v213, 0
	v_mov_b32_e32 v214, 0
	v_mov_b32_e32 v215, 0
	v_mov_b32_e32 v216, 0
	v_mov_b32_e32 v217, 0
	v_mov_b32_e32 v218, 0
	v_mov_b32_e32 v219, 0
	v_mov_b32_e32 v220, 0
	v_mov_b32_e32 v221, 0
	v_mov_b32_e32 v222, 0
	v_mov_b32_e32 v223, 0
	s_waitcnt vmcnt(0)
	v_add_f32_e32 v20, 1.0, v20
	v_add_f32_e32 v21, 1.0, v21
	v_add_f32_e32 v22, 1.0, v22
	v_add_f32_e32 v23, 1.0, v23
	v_mul_f32_e32 v20, v24, v20
	v_mul_f32_e32 v21, v25, v21
	v_mul_f32_e32 v22, v26, v22
	v_mul_f32_e32 v23, v27, v23
; template <int W>
; __device__ __forceinline__ void pool_chunk(const float* x, bf16_t* P, const LAS float* rs  , const f32x4 gs, const f32x4 sh, size_t r0, bool has_halo, int tid) {
;     ...
;     for (int i0 = 0; i0 < 128; i0 += 16) {
;         f32x4 xv[16];
; #pragma unroll
;         for (int jj = 0; jj < 16; ++jj) xv[jj] = *(const f32x4*)(xp + (size_t)(i0 + jj) * D);
; __device__ void phase1(const Params& p, LAS unsigned char* lds) {
;     ...
;         for (int t = (has_halo ? -15 : 0) + wave; t < 128; t += 8) {
;             const float* xr = p.x + (r0 + t) * D + lane * 4; float ss = 0.f;
; #pragma unroll
;             for (int i = 0; i < 8; ++i) { const f32x4 v = *(const f32x4*)(xr + i * 256); ss += v[0] * v[0] + v[1] * v[1] + v[2] * v[2] + v[3] * v[3]; }
;             ss = wave_sum(ss);
;             if (lane == 0) rs[t + 15] = 1.0f / sqrtf(ss * (1.0f / D) + EPS);
.Lp1_group:
	global_load_dwordx4 v[60:63], v28, s[30:31]
	global_load_dwordx4 v[64:67], v29, s[30:31]
	global_load_dwordx4 v[68:71], v30, s[30:31]
	global_load_dwordx4 v[72:75], v31, s[30:31]
	global_load_dwordx4 v[76:79], v32, s[30:31]
	global_load_dwordx4 v[80:83], v33, s[30:31]
	global_load_dwordx4 v[84:87], v34, s[30:31]
	global_load_dwordx4 v[88:91], v35, s[30:31]
	global_load_dwordx4 v[92:95], v36, s[30:31]
	global_load_dwordx4 v[96:99], v37, s[30:31]
	global_load_dwordx4 v[100:103], v38, s[30:31]
	global_load_dwordx4 v[104:107], v39, s[30:31]
	global_load_dwordx4 v[108:111], v40, s[30:31]
	global_load_dwordx4 v[112:115], v41, s[30:31]
	global_load_dwordx4 v[116:119], v42, s[30:31]
	global_load_dwordx4 v[120:123], v43, s[30:31]
	s_waitcnt vmcnt(15)
	v_mul_f32_e32 v124, v60, v60
	v_fmac_f32_e32 v124, v61, v61
	v_fmac_f32_e32 v124, v62, v62
	v_fmac_f32_e32 v124, v63, v63
	s_waitcnt vmcnt(14)
	v_mul_f32_e32 v125, v64, v64
	v_fmac_f32_e32 v125, v65, v65
	v_fmac_f32_e32 v125, v66, v66
	v_fmac_f32_e32 v125, v67, v67
	s_waitcnt vmcnt(13)
	v_mul_f32_e32 v126, v68, v68
	v_fmac_f32_e32 v126, v69, v69
	v_fmac_f32_e32 v126, v70, v70
	v_fmac_f32_e32 v126, v71, v71
	s_waitcnt vmcnt(12)
	v_mul_f32_e32 v127, v72, v72
	v_fmac_f32_e32 v127, v73, v73
	v_fmac_f32_e32 v127, v74, v74
	v_fmac_f32_e32 v127, v75, v75
	s_waitcnt vmcnt(11)
	v_mul_f32_e32 v128, v76, v76
	v_fmac_f32_e32 v128, v77, v77
	v_fmac_f32_e32 v128, v78, v78
	v_fmac_f32_e32 v128, v79, v79
	s_waitcnt vmcnt(10)
	v_mul_f32_e32 v129, v80, v80
	v_fmac_f32_e32 v129, v81, v81
	v_fmac_f32_e32 v129, v82, v82
	v_fmac_f32_e32 v129, v83, v83
	s_waitcnt vmcnt(9)
	v_mul_f32_e32 v130, v84, v84
	v_fmac_f32_e32 v130, v85, v85
	v_fmac_f32_e32 v130, v86, v86
	v_fmac_f32_e32 v130, v87, v87
	s_waitcnt vmcnt(8)
	v_mul_f32_e32 v131, v88, v88
	v_fmac_f32_e32 v131, v89, v89
	v_fmac_f32_e32 v131, v90, v90
	v_fmac_f32_e32 v131, v91, v91
	s_waitcnt vmcnt(7)
	v_mul_f32_e32 v132, v92, v92
	v_fmac_f32_e32 v132, v93, v93
	v_fmac_f32_e32 v132, v94, v94
	v_fmac_f32_e32 v132, v95, v95
	s_waitcnt vmcnt(6)
	v_mul_f32_e32 v133, v96, v96
	v_fmac_f32_e32 v133, v97, v97
	v_fmac_f32_e32 v133, v98, v98
	v_fmac_f32_e32 v133, v99, v99
	s_waitcnt vmcnt(5)
	v_mul_f32_e32 v134, v100, v100
	v_fmac_f32_e32 v134, v101, v101
	v_fmac_f32_e32 v134, v102, v102
	v_fmac_f32_e32 v134, v103, v103
	s_waitcnt vmcnt(4)
	v_mul_f32_e32 v135, v104, v104
	v_fmac_f32_e32 v135, v105, v105
	v_fmac_f32_e32 v135, v106, v106
	v_fmac_f32_e32 v135, v107, v107
	s_waitcnt vmcnt(3)
	v_mul_f32_e32 v136, v108, v108
	v_fmac_f32_e32 v136, v109, v109
	v_fmac_f32_e32 v136, v110, v110
	v_fmac_f32_e32 v136, v111, v111
	s_waitcnt vmcnt(2)
	v_mul_f32_e32 v137, v112, v112
	v_fmac_f32_e32 v137, v113, v113
	v_fmac_f32_e32 v137, v114, v114
	v_fmac_f32_e32 v137, v115, v115
	s_waitcnt vmcnt(1)
	v_mul_f32_e32 v138, v116, v116
	v_fmac_f32_e32 v138, v117, v117
	v_fmac_f32_e32 v138, v118, v118
	v_fmac_f32_e32 v138, v119, v119
	s_waitcnt vmcnt(0)
	v_mul_f32_e32 v139, v120, v120
	v_fmac_f32_e32 v139, v121, v121
	v_fmac_f32_e32 v139, v122, v122
	v_fmac_f32_e32 v139, v123, v123
	ds_write_b32 v46, v124 offset:0
	ds_write_b32 v46, v125 offset:2048
	ds_write_b32 v46, v126 offset:4096
	ds_write_b32 v46, v127 offset:6144
	ds_write_b32 v46, v128 offset:8192
	ds_write_b32 v46, v129 offset:10240
	ds_write_b32 v46, v130 offset:12288
	ds_write_b32 v46, v131 offset:14336
	ds_write_b32 v46, v132 offset:16384
	ds_write_b32 v46, v133 offset:18432
	ds_write_b32 v46, v134 offset:20480
	ds_write_b32 v46, v135 offset:22528
	ds_write_b32 v46, v136 offset:24576
	ds_write_b32 v46, v137 offset:26624
	ds_write_b32 v46, v138 offset:28672
	ds_write_b32 v46, v139 offset:30720
	s_waitcnt lgkmcnt(0)
	s_barrier
	ds_read_b32 v124, v47 offset:0
	ds_read_b32 v125, v47 offset:256
	ds_read_b32 v126, v47 offset:512
	ds_read_b32 v127, v47 offset:768
	ds_read_b32 v128, v47 offset:1024
	ds_read_b32 v129, v47 offset:1280
	ds_read_b32 v130, v47 offset:1536
	ds_read_b32 v131, v47 offset:1792
	ds_read_b32 v132, v47 offset:2048
	ds_read_b32 v133, v47 offset:2304
	ds_read_b32 v134, v47 offset:2560
	ds_read_b32 v135, v47 offset:2816
	ds_read_b32 v136, v47 offset:3072
	ds_read_b32 v137, v47 offset:3328
	ds_read_b32 v138, v47 offset:3584
	ds_read_b32 v139, v47 offset:3840
	s_waitcnt lgkmcnt(0)
	v_add_f32_e32 v124, v124, v125
	v_add_f32_e32 v126, v126, v127
	v_add_f32_e32 v128, v128, v129
	v_add_f32_e32 v130, v130, v131
	v_add_f32_e32 v124, v124, v126
	v_add_f32_e32 v128, v128, v130
	v_add_f32_e32 v124, v124, v128
	v_add_f32_e32 v132, v132, v133
	v_add_f32_e32 v134, v134, v135
	v_add_f32_e32 v136, v136, v137
	v_add_f32_e32 v138, v138, v139
	v_add_f32_e32 v132, v132, v134
	v_add_f32_e32 v136, v136, v138
	v_add_f32_e32 v132, v132, v136
	ds_bpermute_b32 v125, v48, v124
	ds_bpermute_b32 v133, v48, v132
	s_waitcnt lgkmcnt(1)
	v_add_f32_e32 v124, v124, v125
	s_waitcnt lgkmcnt(0)
	v_add_f32_e32 v132, v132, v133
	ds_bpermute_b32 v125, v49, v124
	ds_bpermute_b32 v133, v49, v132
	s_waitcnt lgkmcnt(1)
	v_add_f32_e32 v124, v124, v125
	s_waitcnt lgkmcnt(0)
	v_add_f32_e32 v132, v132, v133
	ds_bpermute_b32 v125, v50, v124
	ds_bpermute_b32 v133, v50, v132
	s_waitcnt lgkmcnt(1)
	v_add_f32_e32 v124, v124, v125
	s_waitcnt lgkmcnt(0)
	v_add_f32_e32 v132, v132, v133
	ds_bpermute_b32 v125, v51, v124
	ds_bpermute_b32 v133, v51, v132
	s_waitcnt lgkmcnt(1)
	v_add_f32_e32 v124, v124, v125
	s_waitcnt lgkmcnt(0)
	v_add_f32_e32 v132, v132, v133
	ds_bpermute_b32 v125, v52, v124
	ds_bpermute_b32 v133, v52, v132
	s_waitcnt lgkmcnt(1)
	v_add_f32_e32 v124, v124, v125
	s_waitcnt lgkmcnt(0)
	v_add_f32_e32 v132, v132, v133
	ds_bpermute_b32 v125, v53, v124
	ds_bpermute_b32 v133, v53, v132
	s_waitcnt lgkmcnt(1)
; __device__ __forceinline__ unsigned cvt_pk_bf16(float lo, float hi) { unsigned r; asm volatile("v_cvt_pk_bf16_f32 %0, %1, %2" : "=v"(r) : "v"(lo), "v"(hi)); return r; }
; template <int W>
; __device__ __forceinline__ void pool_chunk(const float* x, bf16_t* P, const LAS float* rs  , const f32x4 gs, const f32x4 sh, size_t r0, bool has_halo, int tid) {
;     ...
;         for (int jj = 0; jj < 16; ++jj) { const int i = i0 + jj; constexpr int dummy = 0; (void)dummy;
;             const int slot = (W - 1 + jj) % W;
;             const f32x4 h = xv[jj] * rs[i + 15] * gs + sh;
;             s += h - ring[slot]; ring[slot] = h;
;             const float inv = has_halo ? (1.0f / W) : (1.0f / (float)((i + 1) < W ? (i + 1) : W));
;             const f32x4 o = s * inv - h;
;             u32x2 w; w.x = cvt_pk_bf16(o[0], o[1]); w.y = cvt_pk_bf16(o[2], o[3]);
;             *(u32x2*)(P + img_off((int)(r0 + i), tid * 4, D)) = w; }
; __device__ void phase1(const Params& p, LAS unsigned char* lds) {
;     ...
;             if (lane == 0) rs[t + 15] = 1.0f / sqrtf(ss * (1.0f / D) + EPS);
;         }
;         __syncthreads();
;         const f32x4 g4 = *(const f32x4*)(p.n1g + tid * 4);
;         const f32x4 sc = *(const f32x4*)(mod + (size_t)b * MODW + 1 * D + tid * 4), sh = *(const f32x4*)(mod + (size_t)b * MODW + 0 * D + tid * 4);
;         const f32x4 gs = g4 * (sc + 1.0f);
;         const int grp = tid >> 7;
;         if (grp == 0) pool_chunk<2>(p.x, P, rs, gs, sh, r0, has_halo, tid);
;         else if (grp == 1) pool_chunk<4>(p.x, P, rs, gs, sh, r0, has_halo, tid);
;         else if (grp == 2) pool_chunk<8>(p.x, P, rs, gs, sh, r0, has_halo, tid);
;         else pool_chunk<16>(p.x, P, rs, gs, sh, r0, has_halo, tid);
	v_add_f32_e32 v124, v124, v125
	s_waitcnt lgkmcnt(0)
	v_add_f32_e32 v132, v132, v133
	v_fmamk_f32 v124, v124, 0x3a000000, v54
	v_mul_f32_e32 v224, 0x4f800000, v124
	v_cmp_gt_f32_e32 vcc, s54, v124
	s_nop 1
	v_cndmask_b32_e32 v124, v124, v224, vcc
	v_sqrt_f32_e32 v224, v124
	s_nop 0
	v_add_u32_e32 v225, -1, v224
	v_fma_f32 v227, -v225, v224, v124
	v_add_u32_e32 v226, 1, v224
	v_cmp_ge_f32_e64 s[52:53], 0, v227
	s_nop 1
	v_cndmask_b32_e64 v225, v224, v225, s[52:53]
	v_fma_f32 v224, -v226, v224, v124
	v_cmp_lt_f32_e64 s[52:53], 0, v224
	s_nop 1
	v_cndmask_b32_e64 v224, v225, v226, s[52:53]
	v_mul_f32_e32 v225, 0x37800000, v224
	v_cndmask_b32_e32 v224, v224, v225, vcc
	v_cmp_class_f32_e32 vcc, v124, v55
	s_nop 1
	v_cndmask_b32_e32 v124, v224, v124, vcc
	v_div_scale_f32 v224, s[52:53], v124, v124, 1.0
	v_rcp_f32_e32 v225, v224
	s_nop 0
	v_fma_f32 v226, -v224, v225, 1.0
	v_fmac_f32_e32 v225, v226, v225
	v_div_scale_f32 v226, vcc, 1.0, v124, 1.0
	v_mul_f32_e32 v227, v226, v225
	v_fma_f32 v228, -v224, v227, v226
	v_fmac_f32_e32 v227, v228, v225
	v_fma_f32 v224, -v224, v227, v226
	v_div_fmas_f32 v224, v224, v225, v227
	v_div_fixup_f32 v124, v224, v124, 1.0
	v_fmamk_f32 v132, v132, 0x3a000000, v54
	v_mul_f32_e32 v224, 0x4f800000, v132
	v_cmp_gt_f32_e32 vcc, s54, v132
	s_nop 1
	v_cndmask_b32_e32 v132, v132, v224, vcc
	v_sqrt_f32_e32 v224, v132
	s_nop 0
	v_add_u32_e32 v225, -1, v224
	v_fma_f32 v227, -v225, v224, v132
	v_add_u32_e32 v226, 1, v224
	v_cmp_ge_f32_e64 s[52:53], 0, v227
	s_nop 1
	v_cndmask_b32_e64 v225, v224, v225, s[52:53]
	v_fma_f32 v224, -v226, v224, v132
	v_cmp_lt_f32_e64 s[52:53], 0, v224
	s_nop 1
	v_cndmask_b32_e64 v224, v225, v226, s[52:53]
	v_mul_f32_e32 v225, 0x37800000, v224
	v_cndmask_b32_e32 v224, v224, v225, vcc
	v_cmp_class_f32_e32 vcc, v132, v55
	s_nop 1
	v_cndmask_b32_e32 v132, v224, v132, vcc
	v_div_scale_f32 v224, s[52:53], v132, v132, 1.0
	v_rcp_f32_e32 v225, v224
	s_nop 0
	v_fma_f32 v226, -v224, v225, 1.0
	v_fmac_f32_e32 v225, v226, v225
	v_div_scale_f32 v226, vcc, 1.0, v132, 1.0
	v_mul_f32_e32 v227, v226, v225
	v_fma_f32 v228, -v224, v227, v226
	v_fmac_f32_e32 v227, v228, v225
	v_fma_f32 v224, -v224, v227, v226
	v_div_fmas_f32 v224, v224, v225, v227
	v_div_fixup_f32 v132, v224, v132, 1.0
	ds_write_b32 v58, v124
	ds_write_b32 v58, v132 offset:4
	s_waitcnt lgkmcnt(0)
	s_barrier
	ds_read_b128 v[140:143], v59 offset:0
	ds_read_b128 v[144:147], v59 offset:16
	ds_read_b128 v[148:151], v59 offset:32
	ds_read_b128 v[152:155], v59 offset:48
	s_waitcnt lgkmcnt(0)
	s_cmp_eq_u32 s69, 0
	s_cbranch_scc1 .Lp1_w2
	s_cmp_eq_u32 s69, 1
	s_cbranch_scc1 .Lp1_w4
	s_cmp_eq_u32 s69, 2
	s_cbranch_scc1 .Lp1_w8
.Lp1_w16:
	s_mov_b32 s55, 0x3d800000
	v_mul_f32_e32 v224, v60, v140
	v_mul_f32_e32 v225, v61, v140
	v_mul_f32_e32 v226, v62, v140
	v_mul_f32_e32 v227, v63, v140
	v_fma_f32 v224, v20, v224, v16
	v_fma_f32 v225, v21, v225, v17
	v_fma_f32 v226, v22, v226, v18
	v_fma_f32 v227, v23, v227, v19
	v_sub_f32_e32 v228, v224, v156
	v_sub_f32_e32 v229, v225, v157
	v_sub_f32_e32 v230, v226, v158
	v_sub_f32_e32 v231, v227, v159
	v_add_f32_e32 v220, v220, v228
	v_add_f32_e32 v221, v221, v229
	v_add_f32_e32 v222, v222, v230
	v_add_f32_e32 v223, v223, v231
	v_mov_b32_e32 v156, v224
	v_mov_b32_e32 v157, v225
	v_mov_b32_e32 v158, v226
	v_mov_b32_e32 v159, v227
	s_cmp_lg_u32 s41, 0
	s_cselect_b32 s57, 0x3f800000, s55
	v_fma_f32 v228, v220, s57, -v224
	v_fma_f32 v229, v221, s57, -v225
	v_fma_f32 v230, v222, s57, -v226
	v_fma_f32 v231, v223, s57, -v227
	v_cvt_pk_bf16_f32 v56, v228, v229
	v_cvt_pk_bf16_f32 v57, v230, v231
	s_mov_b64 exec, s[38:39]
	global_store_dwordx2 v44, v[56:57], s[36:37] offset:0
	s_mov_b64 exec, -1
	v_mul_f32_e32 v224, v64, v141
	v_mul_f32_e32 v225, v65, v141
	v_mul_f32_e32 v226, v66, v141
	v_mul_f32_e32 v227, v67, v141
	v_fma_f32 v224, v20, v224, v16
	v_fma_f32 v225, v21, v225, v17
	v_fma_f32 v226, v22, v226, v18
	v_fma_f32 v227, v23, v227, v19
	v_sub_f32_e32 v228, v224, v160
	v_sub_f32_e32 v229, v225, v161
	v_sub_f32_e32 v230, v226, v162
	v_sub_f32_e32 v231, v227, v163
	v_add_f32_e32 v220, v220, v228
	v_add_f32_e32 v221, v221, v229
	v_add_f32_e32 v222, v222, v230
	v_add_f32_e32 v223, v223, v231
	v_mov_b32_e32 v160, v224
	v_mov_b32_e32 v161, v225
	v_mov_b32_e32 v162, v226
	v_mov_b32_e32 v163, v227
	s_cmp_lg_u32 s41, 0
	s_cselect_b32 s57, 0x3f000000, s55
	v_fma_f32 v228, v220, s57, -v224
	v_fma_f32 v229, v221, s57, -v225
	v_fma_f32 v230, v222, s57, -v226
	v_fma_f32 v231, v223, s57, -v227
	v_cvt_pk_bf16_f32 v232, v228, v229
	v_cvt_pk_bf16_f32 v233, v230, v231
	s_mov_b64 exec, s[38:39]
	global_store_dwordx2 v44, v[232:233], s[36:37] offset:64
	s_mov_b64 exec, -1
	v_mul_f32_e32 v224, v68, v142
	v_mul_f32_e32 v225, v69, v142
	v_mul_f32_e32 v226, v70, v142
	v_mul_f32_e32 v227, v71, v142
	v_fma_f32 v224, v20, v224, v16
	v_fma_f32 v225, v21, v225, v17
	v_fma_f32 v226, v22, v226, v18
	v_fma_f32 v227, v23, v227, v19
	v_sub_f32_e32 v228, v224, v164
	v_sub_f32_e32 v229, v225, v165
	v_sub_f32_e32 v230, v226, v166
	v_sub_f32_e32 v231, v227, v167
	v_add_f32_e32 v220, v220, v228
	v_add_f32_e32 v221, v221, v229
	v_add_f32_e32 v222, v222, v230
	v_add_f32_e32 v223, v223, v231
	v_mov_b32_e32 v164, v224
	v_mov_b32_e32 v165, v225
	v_mov_b32_e32 v166, v226
	v_mov_b32_e32 v167, v227
	s_cmp_lg_u32 s41, 0
	s_cselect_b32 s57, 0x3eaaaaab, s55
	v_fma_f32 v228, v220, s57, -v224
	v_fma_f32 v229, v221, s57, -v225
	v_fma_f32 v230, v222, s57, -v226
	v_fma_f32 v231, v223, s57, -v227
	v_cvt_pk_bf16_f32 v56, v228, v229
	v_cvt_pk_bf16_f32 v57, v230, v231
	s_mov_b64 exec, s[38:39]
	global_store_dwordx2 v44, v[56:57], s[36:37] offset:128
	s_mov_b64 exec, -1
; __device__ __forceinline__ unsigned cvt_pk_bf16(float lo, float hi) { unsigned r; asm volatile("v_cvt_pk_bf16_f32 %0, %1, %2" : "=v"(r) : "v"(lo), "v"(hi)); return r; }
; template <int W>
; __device__ __forceinline__ void pool_chunk(const float* x, bf16_t* P, const LAS float* rs  , const f32x4 gs, const f32x4 sh, size_t r0, bool has_halo, int tid) {
;     ...
;         for (int jj = 0; jj < 16; ++jj) { const int i = i0 + jj; constexpr int dummy = 0; (void)dummy;
;             const int slot = (W - 1 + jj) % W;
;             const f32x4 h = xv[jj] * rs[i + 15] * gs + sh;
;             s += h - ring[slot]; ring[slot] = h;
;             const float inv = has_halo ? (1.0f / W) : (1.0f / (float)((i + 1) < W ? (i + 1) : W));
;             const f32x4 o = s * inv - h;
;             u32x2 w; w.x = cvt_pk_bf16(o[0], o[1]); w.y = cvt_pk_bf16(o[2], o[3]);
;             *(u32x2*)(P + img_off((int)(r0 + i), tid * 4, D)) = w; }
	v_mul_f32_e32 v224, v72, v143
	v_mul_f32_e32 v225, v73, v143
	v_mul_f32_e32 v226, v74, v143
	v_mul_f32_e32 v227, v75, v143
	v_fma_f32 v224, v20, v224, v16
	v_fma_f32 v225, v21, v225, v17
	v_fma_f32 v226, v22, v226, v18
	v_fma_f32 v227, v23, v227, v19
	v_sub_f32_e32 v228, v224, v168
	v_sub_f32_e32 v229, v225, v169
	v_sub_f32_e32 v230, v226, v170
	v_sub_f32_e32 v231, v227, v171
	v_add_f32_e32 v220, v220, v228
	v_add_f32_e32 v221, v221, v229
	v_add_f32_e32 v222, v222, v230
	v_add_f32_e32 v223, v223, v231
	v_mov_b32_e32 v168, v224
	v_mov_b32_e32 v169, v225
	v_mov_b32_e32 v170, v226
	v_mov_b32_e32 v171, v227
	s_cmp_lg_u32 s41, 0
	s_cselect_b32 s57, 0x3e800000, s55
	v_fma_f32 v228, v220, s57, -v224
	v_fma_f32 v229, v221, s57, -v225
	v_fma_f32 v230, v222, s57, -v226
	v_fma_f32 v231, v223, s57, -v227
	v_cvt_pk_bf16_f32 v232, v228, v229
	v_cvt_pk_bf16_f32 v233, v230, v231
	s_mov_b64 exec, s[38:39]
	global_store_dwordx2 v44, v[232:233], s[36:37] offset:192
	s_mov_b64 exec, -1
	v_mul_f32_e32 v224, v76, v144
	v_mul_f32_e32 v225, v77, v144
	v_mul_f32_e32 v226, v78, v144
	v_mul_f32_e32 v227, v79, v144
	v_fma_f32 v224, v20, v224, v16
	v_fma_f32 v225, v21, v225, v17
	v_fma_f32 v226, v22, v226, v18
	v_fma_f32 v227, v23, v227, v19
	v_sub_f32_e32 v228, v224, v172
	v_sub_f32_e32 v229, v225, v173
	v_sub_f32_e32 v230, v226, v174
	v_sub_f32_e32 v231, v227, v175
	v_add_f32_e32 v220, v220, v228
	v_add_f32_e32 v221, v221, v229
	v_add_f32_e32 v222, v222, v230
	v_add_f32_e32 v223, v223, v231
	v_mov_b32_e32 v172, v224
	v_mov_b32_e32 v173, v225
	v_mov_b32_e32 v174, v226
	v_mov_b32_e32 v175, v227
	s_cmp_lg_u32 s41, 0
	s_cselect_b32 s57, 0x3e4ccccd, s55
	v_fma_f32 v228, v220, s57, -v224
	v_fma_f32 v229, v221, s57, -v225
	v_fma_f32 v230, v222, s57, -v226
	v_fma_f32 v231, v223, s57, -v227
	v_cvt_pk_bf16_f32 v56, v228, v229
	v_cvt_pk_bf16_f32 v57, v230, v231
	s_mov_b64 exec, s[38:39]
	global_store_dwordx2 v44, v[56:57], s[36:37] offset:256
	s_mov_b64 exec, -1
	v_mul_f32_e32 v224, v80, v145
	v_mul_f32_e32 v225, v81, v145
	v_mul_f32_e32 v226, v82, v145
	v_mul_f32_e32 v227, v83, v145
	v_fma_f32 v224, v20, v224, v16
	v_fma_f32 v225, v21, v225, v17
	v_fma_f32 v226, v22, v226, v18
	v_fma_f32 v227, v23, v227, v19
	v_sub_f32_e32 v228, v224, v176
	v_sub_f32_e32 v229, v225, v177
	v_sub_f32_e32 v230, v226, v178
	v_sub_f32_e32 v231, v227, v179
	v_add_f32_e32 v220, v220, v228
	v_add_f32_e32 v221, v221, v229
	v_add_f32_e32 v222, v222, v230
	v_add_f32_e32 v223, v223, v231
	v_mov_b32_e32 v176, v224
	v_mov_b32_e32 v177, v225
	v_mov_b32_e32 v178, v226
	v_mov_b32_e32 v179, v227
	s_cmp_lg_u32 s41, 0
	s_cselect_b32 s57, 0x3e2aaaab, s55
	v_fma_f32 v228, v220, s57, -v224
	v_fma_f32 v229, v221, s57, -v225
	v_fma_f32 v230, v222, s57, -v226
	v_fma_f32 v231, v223, s57, -v227
	v_cvt_pk_bf16_f32 v232, v228, v229
	v_cvt_pk_bf16_f32 v233, v230, v231
	s_mov_b64 exec, s[38:39]
	global_store_dwordx2 v44, v[232:233], s[36:37] offset:320
	s_mov_b64 exec, -1
	v_mul_f32_e32 v224, v84, v146
	v_mul_f32_e32 v225, v85, v146
	v_mul_f32_e32 v226, v86, v146
	v_mul_f32_e32 v227, v87, v146
	v_fma_f32 v224, v20, v224, v16
	v_fma_f32 v225, v21, v225, v17
	v_fma_f32 v226, v22, v226, v18
	v_fma_f32 v227, v23, v227, v19
	v_sub_f32_e32 v228, v224, v180
	v_sub_f32_e32 v229, v225, v181
	v_sub_f32_e32 v230, v226, v182
	v_sub_f32_e32 v231, v227, v183
	v_add_f32_e32 v220, v220, v228
	v_add_f32_e32 v221, v221, v229
	v_add_f32_e32 v222, v222, v230
	v_add_f32_e32 v223, v223, v231
	v_mov_b32_e32 v180, v224
	v_mov_b32_e32 v181, v225
	v_mov_b32_e32 v182, v226
	v_mov_b32_e32 v183, v227
	s_cmp_lg_u32 s41, 0
	s_cselect_b32 s57, 0x3e124925, s55
	v_fma_f32 v228, v220, s57, -v224
	v_fma_f32 v229, v221, s57, -v225
	v_fma_f32 v230, v222, s57, -v226
	v_fma_f32 v231, v223, s57, -v227
	v_cvt_pk_bf16_f32 v56, v228, v229
	v_cvt_pk_bf16_f32 v57, v230, v231
	s_mov_b64 exec, s[38:39]
	global_store_dwordx2 v44, v[56:57], s[36:37] offset:384
	s_mov_b64 exec, -1
	v_mul_f32_e32 v224, v88, v147
	v_mul_f32_e32 v225, v89, v147
	v_mul_f32_e32 v226, v90, v147
	v_mul_f32_e32 v227, v91, v147
	v_fma_f32 v224, v20, v224, v16
	v_fma_f32 v225, v21, v225, v17
	v_fma_f32 v226, v22, v226, v18
	v_fma_f32 v227, v23, v227, v19
	v_sub_f32_e32 v228, v224, v184
	v_sub_f32_e32 v229, v225, v185
	v_sub_f32_e32 v230, v226, v186
	v_sub_f32_e32 v231, v227, v187
	v_add_f32_e32 v220, v220, v228
	v_add_f32_e32 v221, v221, v229
	v_add_f32_e32 v222, v222, v230
	v_add_f32_e32 v223, v223, v231
	v_mov_b32_e32 v184, v224
	v_mov_b32_e32 v185, v225
	v_mov_b32_e32 v186, v226
	v_mov_b32_e32 v187, v227
	s_cmp_lg_u32 s41, 0
	s_cselect_b32 s57, 0x3e000000, s55
	v_fma_f32 v228, v220, s57, -v224
	v_fma_f32 v229, v221, s57, -v225
	v_fma_f32 v230, v222, s57, -v226
	v_fma_f32 v231, v223, s57, -v227
	v_cvt_pk_bf16_f32 v232, v228, v229
	v_cvt_pk_bf16_f32 v233, v230, v231
	s_mov_b64 exec, s[38:39]
	global_store_dwordx2 v44, v[232:233], s[36:37] offset:448
	s_mov_b64 exec, -1
	v_mul_f32_e32 v224, v92, v148
	v_mul_f32_e32 v225, v93, v148
	v_mul_f32_e32 v226, v94, v148
	v_mul_f32_e32 v227, v95, v148
	v_fma_f32 v224, v20, v224, v16
	v_fma_f32 v225, v21, v225, v17
	v_fma_f32 v226, v22, v226, v18
	v_fma_f32 v227, v23, v227, v19
	v_sub_f32_e32 v228, v224, v188
	v_sub_f32_e32 v229, v225, v189
	v_sub_f32_e32 v230, v226, v190
	v_sub_f32_e32 v231, v227, v191
	v_add_f32_e32 v220, v220, v228
	v_add_f32_e32 v221, v221, v229
	v_add_f32_e32 v222, v222, v230
	v_add_f32_e32 v223, v223, v231
	v_mov_b32_e32 v188, v224
	v_mov_b32_e32 v189, v225
	v_mov_b32_e32 v190, v226
	v_mov_b32_e32 v191, v227
	s_cmp_lg_u32 s41, 0
	s_cselect_b32 s57, 0x3de38e39, s55
	v_fma_f32 v228, v220, s57, -v224
	v_fma_f32 v229, v221, s57, -v225
; __device__ __forceinline__ unsigned cvt_pk_bf16(float lo, float hi) { unsigned r; asm volatile("v_cvt_pk_bf16_f32 %0, %1, %2" : "=v"(r) : "v"(lo), "v"(hi)); return r; }
; template <int W>
; __device__ __forceinline__ void pool_chunk(const float* x, bf16_t* P, const LAS float* rs  , const f32x4 gs, const f32x4 sh, size_t r0, bool has_halo, int tid) {
;     ...
;         for (int jj = 0; jj < 16; ++jj) { const int i = i0 + jj; constexpr int dummy = 0; (void)dummy;
;             const int slot = (W - 1 + jj) % W;
;             const f32x4 h = xv[jj] * rs[i + 15] * gs + sh;
;             s += h - ring[slot]; ring[slot] = h;
;             const float inv = has_halo ? (1.0f / W) : (1.0f / (float)((i + 1) < W ? (i + 1) : W));
;             const f32x4 o = s * inv - h;
;             u32x2 w; w.x = cvt_pk_bf16(o[0], o[1]); w.y = cvt_pk_bf16(o[2], o[3]);
;             *(u32x2*)(P + img_off((int)(r0 + i), tid * 4, D)) = w; }
	v_fma_f32 v230, v222, s57, -v226
	v_fma_f32 v231, v223, s57, -v227
	v_cvt_pk_bf16_f32 v56, v228, v229
	v_cvt_pk_bf16_f32 v57, v230, v231
	s_mov_b64 exec, s[38:39]
	global_store_dwordx2 v45, v[56:57], s[36:37] offset:512
	s_mov_b64 exec, -1
	v_mul_f32_e32 v224, v96, v149
	v_mul_f32_e32 v225, v97, v149
	v_mul_f32_e32 v226, v98, v149
	v_mul_f32_e32 v227, v99, v149
	v_fma_f32 v224, v20, v224, v16
	v_fma_f32 v225, v21, v225, v17
	v_fma_f32 v226, v22, v226, v18
	v_fma_f32 v227, v23, v227, v19
	v_sub_f32_e32 v228, v224, v192
	v_sub_f32_e32 v229, v225, v193
	v_sub_f32_e32 v230, v226, v194
	v_sub_f32_e32 v231, v227, v195
	v_add_f32_e32 v220, v220, v228
	v_add_f32_e32 v221, v221, v229
	v_add_f32_e32 v222, v222, v230
	v_add_f32_e32 v223, v223, v231
	v_mov_b32_e32 v192, v224
	v_mov_b32_e32 v193, v225
	v_mov_b32_e32 v194, v226
	v_mov_b32_e32 v195, v227
	s_cmp_lg_u32 s41, 0
	s_cselect_b32 s57, 0x3dcccccd, s55
	v_fma_f32 v228, v220, s57, -v224
	v_fma_f32 v229, v221, s57, -v225
	v_fma_f32 v230, v222, s57, -v226
	v_fma_f32 v231, v223, s57, -v227
	v_cvt_pk_bf16_f32 v232, v228, v229
	v_cvt_pk_bf16_f32 v233, v230, v231
	s_mov_b64 exec, s[38:39]
	global_store_dwordx2 v45, v[232:233], s[36:37] offset:576
	s_mov_b64 exec, -1
	v_mul_f32_e32 v224, v100, v150
	v_mul_f32_e32 v225, v101, v150
	v_mul_f32_e32 v226, v102, v150
	v_mul_f32_e32 v227, v103, v150
	v_fma_f32 v224, v20, v224, v16
	v_fma_f32 v225, v21, v225, v17
	v_fma_f32 v226, v22, v226, v18
	v_fma_f32 v227, v23, v227, v19
	v_sub_f32_e32 v228, v224, v196
	v_sub_f32_e32 v229, v225, v197
	v_sub_f32_e32 v230, v226, v198
	v_sub_f32_e32 v231, v227, v199
	v_add_f32_e32 v220, v220, v228
	v_add_f32_e32 v221, v221, v229
	v_add_f32_e32 v222, v222, v230
	v_add_f32_e32 v223, v223, v231
	v_mov_b32_e32 v196, v224
	v_mov_b32_e32 v197, v225
	v_mov_b32_e32 v198, v226
	v_mov_b32_e32 v199, v227
	s_cmp_lg_u32 s41, 0
	s_cselect_b32 s57, 0x3dba2e8c, s55
	v_fma_f32 v228, v220, s57, -v224
	v_fma_f32 v229, v221, s57, -v225
	v_fma_f32 v230, v222, s57, -v226
	v_fma_f32 v231, v223, s57, -v227
	v_cvt_pk_bf16_f32 v56, v228, v229
	v_cvt_pk_bf16_f32 v57, v230, v231
	s_mov_b64 exec, s[38:39]
	global_store_dwordx2 v45, v[56:57], s[36:37] offset:640
	s_mov_b64 exec, -1
	v_mul_f32_e32 v224, v104, v151
	v_mul_f32_e32 v225, v105, v151
	v_mul_f32_e32 v226, v106, v151
	v_mul_f32_e32 v227, v107, v151
	v_fma_f32 v224, v20, v224, v16
	v_fma_f32 v225, v21, v225, v17
	v_fma_f32 v226, v22, v226, v18
	v_fma_f32 v227, v23, v227, v19
	v_sub_f32_e32 v228, v224, v200
	v_sub_f32_e32 v229, v225, v201
	v_sub_f32_e32 v230, v226, v202
	v_sub_f32_e32 v231, v227, v203
	v_add_f32_e32 v220, v220, v228
	v_add_f32_e32 v221, v221, v229
	v_add_f32_e32 v222, v222, v230
	v_add_f32_e32 v223, v223, v231
	v_mov_b32_e32 v200, v224
	v_mov_b32_e32 v201, v225
	v_mov_b32_e32 v202, v226
	v_mov_b32_e32 v203, v227
	s_cmp_lg_u32 s41, 0
	s_cselect_b32 s57, 0x3daaaaab, s55
	v_fma_f32 v228, v220, s57, -v224
	v_fma_f32 v229, v221, s57, -v225
	v_fma_f32 v230, v222, s57, -v226
	v_fma_f32 v231, v223, s57, -v227
	v_cvt_pk_bf16_f32 v232, v228, v229
	v_cvt_pk_bf16_f32 v233, v230, v231
	s_mov_b64 exec, s[38:39]
	global_store_dwordx2 v45, v[232:233], s[36:37] offset:704
	s_mov_b64 exec, -1
	v_mul_f32_e32 v224, v108, v152
	v_mul_f32_e32 v225, v109, v152
	v_mul_f32_e32 v226, v110, v152
	v_mul_f32_e32 v227, v111, v152
	v_fma_f32 v224, v20, v224, v16
	v_fma_f32 v225, v21, v225, v17
	v_fma_f32 v226, v22, v226, v18
	v_fma_f32 v227, v23, v227, v19
	v_sub_f32_e32 v228, v224, v204
	v_sub_f32_e32 v229, v225, v205
	v_sub_f32_e32 v230, v226, v206
	v_sub_f32_e32 v231, v227, v207
	v_add_f32_e32 v220, v220, v228
	v_add_f32_e32 v221, v221, v229
	v_add_f32_e32 v222, v222, v230
	v_add_f32_e32 v223, v223, v231
	v_mov_b32_e32 v204, v224
	v_mov_b32_e32 v205, v225
	v_mov_b32_e32 v206, v226
	v_mov_b32_e32 v207, v227
	s_cmp_lg_u32 s41, 0
	s_cselect_b32 s57, 0x3d9d89d9, s55
	v_fma_f32 v228, v220, s57, -v224
	v_fma_f32 v229, v221, s57, -v225
	v_fma_f32 v230, v222, s57, -v226
	v_fma_f32 v231, v223, s57, -v227
	v_cvt_pk_bf16_f32 v56, v228, v229
	v_cvt_pk_bf16_f32 v57, v230, v231
	s_mov_b64 exec, s[38:39]
	global_store_dwordx2 v45, v[56:57], s[36:37] offset:768
	s_mov_b64 exec, -1
	v_mul_f32_e32 v224, v112, v153
	v_mul_f32_e32 v225, v113, v153
	v_mul_f32_e32 v226, v114, v153
	v_mul_f32_e32 v227, v115, v153
	v_fma_f32 v224, v20, v224, v16
	v_fma_f32 v225, v21, v225, v17
	v_fma_f32 v226, v22, v226, v18
	v_fma_f32 v227, v23, v227, v19
	v_sub_f32_e32 v228, v224, v208
	v_sub_f32_e32 v229, v225, v209
	v_sub_f32_e32 v230, v226, v210
	v_sub_f32_e32 v231, v227, v211
	v_add_f32_e32 v220, v220, v228
	v_add_f32_e32 v221, v221, v229
	v_add_f32_e32 v222, v222, v230
	v_add_f32_e32 v223, v223, v231
	v_mov_b32_e32 v208, v224
	v_mov_b32_e32 v209, v225
	v_mov_b32_e32 v210, v226
	v_mov_b32_e32 v211, v227
	s_cmp_lg_u32 s41, 0
	s_cselect_b32 s57, 0x3d924925, s55
	v_fma_f32 v228, v220, s57, -v224
	v_fma_f32 v229, v221, s57, -v225
	v_fma_f32 v230, v222, s57, -v226
	v_fma_f32 v231, v223, s57, -v227
	v_cvt_pk_bf16_f32 v232, v228, v229
	v_cvt_pk_bf16_f32 v233, v230, v231
	s_mov_b64 exec, s[38:39]
	global_store_dwordx2 v45, v[232:233], s[36:37] offset:832
	s_mov_b64 exec, -1
	v_mul_f32_e32 v224, v116, v154
	v_mul_f32_e32 v225, v117, v154
	v_mul_f32_e32 v226, v118, v154
	v_mul_f32_e32 v227, v119, v154
	v_fma_f32 v224, v20, v224, v16
	v_fma_f32 v225, v21, v225, v17
	v_fma_f32 v226, v22, v226, v18
	v_fma_f32 v227, v23, v227, v19
	v_sub_f32_e32 v228, v224, v212
	v_sub_f32_e32 v229, v225, v213
	v_sub_f32_e32 v230, v226, v214
	v_sub_f32_e32 v231, v227, v215
	v_add_f32_e32 v220, v220, v228
	v_add_f32_e32 v221, v221, v229
	v_add_f32_e32 v222, v222, v230
; __device__ __forceinline__ unsigned cvt_pk_bf16(float lo, float hi) { unsigned r; asm volatile("v_cvt_pk_bf16_f32 %0, %1, %2" : "=v"(r) : "v"(lo), "v"(hi)); return r; }
; template <int W>
; __device__ __forceinline__ void pool_chunk(const float* x, bf16_t* P, const LAS float* rs  , const f32x4 gs, const f32x4 sh, size_t r0, bool has_halo, int tid) {
;     ...
;         for (int jj = 0; jj < 16; ++jj) { const int i = i0 + jj; constexpr int dummy = 0; (void)dummy;
;             const int slot = (W - 1 + jj) % W;
;             const f32x4 h = xv[jj] * rs[i + 15] * gs + sh;
;             s += h - ring[slot]; ring[slot] = h;
;             const float inv = has_halo ? (1.0f / W) : (1.0f / (float)((i + 1) < W ? (i + 1) : W));
;             const f32x4 o = s * inv - h;
;             u32x2 w; w.x = cvt_pk_bf16(o[0], o[1]); w.y = cvt_pk_bf16(o[2], o[3]);
;             *(u32x2*)(P + img_off((int)(r0 + i), tid * 4, D)) = w; }
	v_add_f32_e32 v223, v223, v231
	v_mov_b32_e32 v212, v224
	v_mov_b32_e32 v213, v225
	v_mov_b32_e32 v214, v226
	v_mov_b32_e32 v215, v227
	s_cmp_lg_u32 s41, 0
	s_cselect_b32 s57, 0x3d888889, s55
	v_fma_f32 v228, v220, s57, -v224
	v_fma_f32 v229, v221, s57, -v225
	v_fma_f32 v230, v222, s57, -v226
	v_fma_f32 v231, v223, s57, -v227
	v_cvt_pk_bf16_f32 v56, v228, v229
	v_cvt_pk_bf16_f32 v57, v230, v231
	s_mov_b64 exec, s[38:39]
	global_store_dwordx2 v45, v[56:57], s[36:37] offset:896
	s_mov_b64 exec, -1
	v_mul_f32_e32 v224, v120, v155
	v_mul_f32_e32 v225, v121, v155
	v_mul_f32_e32 v226, v122, v155
	v_mul_f32_e32 v227, v123, v155
	v_fma_f32 v224, v20, v224, v16
	v_fma_f32 v225, v21, v225, v17
	v_fma_f32 v226, v22, v226, v18
	v_fma_f32 v227, v23, v227, v19
	v_sub_f32_e32 v228, v224, v216
	v_sub_f32_e32 v229, v225, v217
	v_sub_f32_e32 v230, v226, v218
	v_sub_f32_e32 v231, v227, v219
	v_add_f32_e32 v220, v220, v228
	v_add_f32_e32 v221, v221, v229
	v_add_f32_e32 v222, v222, v230
	v_add_f32_e32 v223, v223, v231
	v_mov_b32_e32 v216, v224
	v_mov_b32_e32 v217, v225
	v_mov_b32_e32 v218, v226
	v_mov_b32_e32 v219, v227
	v_fma_f32 v228, v220, s55, -v224
	v_fma_f32 v229, v221, s55, -v225
	v_fma_f32 v230, v222, s55, -v226
	v_fma_f32 v231, v223, s55, -v227
	v_cvt_pk_bf16_f32 v232, v228, v229
	v_cvt_pk_bf16_f32 v233, v230, v231
	s_mov_b64 exec, s[38:39]
	global_store_dwordx2 v45, v[232:233], s[36:37] offset:960
	s_mov_b64 exec, -1
	s_branch .Lp1_join
.Lp1_w8:
	s_mov_b32 s55, 0x3e000000
	v_mul_f32_e32 v224, v60, v140
	v_mul_f32_e32 v225, v61, v140
	v_mul_f32_e32 v226, v62, v140
	v_mul_f32_e32 v227, v63, v140
	v_fma_f32 v224, v20, v224, v16
	v_fma_f32 v225, v21, v225, v17
	v_fma_f32 v226, v22, v226, v18
	v_fma_f32 v227, v23, v227, v19
	v_sub_f32_e32 v228, v224, v156
	v_sub_f32_e32 v229, v225, v157
	v_sub_f32_e32 v230, v226, v158
	v_sub_f32_e32 v231, v227, v159
	v_add_f32_e32 v220, v220, v228
	v_add_f32_e32 v221, v221, v229
	v_add_f32_e32 v222, v222, v230
	v_add_f32_e32 v223, v223, v231
	v_mov_b32_e32 v156, v224
	v_mov_b32_e32 v157, v225
	v_mov_b32_e32 v158, v226
	v_mov_b32_e32 v159, v227
	s_cmp_lg_u32 s41, 0
	s_cselect_b32 s57, 0x3f800000, s55
	v_fma_f32 v228, v220, s57, -v224
	v_fma_f32 v229, v221, s57, -v225
	v_fma_f32 v230, v222, s57, -v226
	v_fma_f32 v231, v223, s57, -v227
	v_cvt_pk_bf16_f32 v56, v228, v229
	v_cvt_pk_bf16_f32 v57, v230, v231
	s_mov_b64 exec, s[38:39]
	global_store_dwordx2 v44, v[56:57], s[36:37] offset:0
	s_mov_b64 exec, -1
	v_mul_f32_e32 v224, v64, v141
	v_mul_f32_e32 v225, v65, v141
	v_mul_f32_e32 v226, v66, v141
	v_mul_f32_e32 v227, v67, v141
	v_fma_f32 v224, v20, v224, v16
	v_fma_f32 v225, v21, v225, v17
	v_fma_f32 v226, v22, v226, v18
	v_fma_f32 v227, v23, v227, v19
	v_sub_f32_e32 v228, v224, v160
	v_sub_f32_e32 v229, v225, v161
	v_sub_f32_e32 v230, v226, v162
	v_sub_f32_e32 v231, v227, v163
	v_add_f32_e32 v220, v220, v228
	v_add_f32_e32 v221, v221, v229
	v_add_f32_e32 v222, v222, v230
	v_add_f32_e32 v223, v223, v231
	v_mov_b32_e32 v160, v224
	v_mov_b32_e32 v161, v225
	v_mov_b32_e32 v162, v226
	v_mov_b32_e32 v163, v227
	s_cmp_lg_u32 s41, 0
	s_cselect_b32 s57, 0x3f000000, s55
	v_fma_f32 v228, v220, s57, -v224
	v_fma_f32 v229, v221, s57, -v225
	v_fma_f32 v230, v222, s57, -v226
	v_fma_f32 v231, v223, s57, -v227
	v_cvt_pk_bf16_f32 v232, v228, v229
	v_cvt_pk_bf16_f32 v233, v230, v231
	s_mov_b64 exec, s[38:39]
	global_store_dwordx2 v44, v[232:233], s[36:37] offset:64
	s_mov_b64 exec, -1
	v_mul_f32_e32 v224, v68, v142
	v_mul_f32_e32 v225, v69, v142
	v_mul_f32_e32 v226, v70, v142
	v_mul_f32_e32 v227, v71, v142
	v_fma_f32 v224, v20, v224, v16
	v_fma_f32 v225, v21, v225, v17
	v_fma_f32 v226, v22, v226, v18
	v_fma_f32 v227, v23, v227, v19
	v_sub_f32_e32 v228, v224, v164
	v_sub_f32_e32 v229, v225, v165
	v_sub_f32_e32 v230, v226, v166
	v_sub_f32_e32 v231, v227, v167
	v_add_f32_e32 v220, v220, v228
	v_add_f32_e32 v221, v221, v229
	v_add_f32_e32 v222, v222, v230
	v_add_f32_e32 v223, v223, v231
	v_mov_b32_e32 v164, v224
	v_mov_b32_e32 v165, v225
	v_mov_b32_e32 v166, v226
	v_mov_b32_e32 v167, v227
	s_cmp_lg_u32 s41, 0
	s_cselect_b32 s57, 0x3eaaaaab, s55
	v_fma_f32 v228, v220, s57, -v224
	v_fma_f32 v229, v221, s57, -v225
	v_fma_f32 v230, v222, s57, -v226
	v_fma_f32 v231, v223, s57, -v227
	v_cvt_pk_bf16_f32 v56, v228, v229
	v_cvt_pk_bf16_f32 v57, v230, v231
	s_mov_b64 exec, s[38:39]
	global_store_dwordx2 v44, v[56:57], s[36:37] offset:128
	s_mov_b64 exec, -1
	v_mul_f32_e32 v224, v72, v143
	v_mul_f32_e32 v225, v73, v143
	v_mul_f32_e32 v226, v74, v143
	v_mul_f32_e32 v227, v75, v143
	v_fma_f32 v224, v20, v224, v16
	v_fma_f32 v225, v21, v225, v17
	v_fma_f32 v226, v22, v226, v18
	v_fma_f32 v227, v23, v227, v19
	v_sub_f32_e32 v228, v224, v168
	v_sub_f32_e32 v229, v225, v169
	v_sub_f32_e32 v230, v226, v170
	v_sub_f32_e32 v231, v227, v171
	v_add_f32_e32 v220, v220, v228
	v_add_f32_e32 v221, v221, v229
	v_add_f32_e32 v222, v222, v230
	v_add_f32_e32 v223, v223, v231
	v_mov_b32_e32 v168, v224
	v_mov_b32_e32 v169, v225
	v_mov_b32_e32 v170, v226
	v_mov_b32_e32 v171, v227
	s_cmp_lg_u32 s41, 0
	s_cselect_b32 s57, 0x3e800000, s55
	v_fma_f32 v228, v220, s57, -v224
	v_fma_f32 v229, v221, s57, -v225
	v_fma_f32 v230, v222, s57, -v226
	v_fma_f32 v231, v223, s57, -v227
	v_cvt_pk_bf16_f32 v232, v228, v229
	v_cvt_pk_bf16_f32 v233, v230, v231
	s_mov_b64 exec, s[38:39]
	global_store_dwordx2 v44, v[232:233], s[36:37] offset:192
	s_mov_b64 exec, -1
	v_mul_f32_e32 v224, v76, v144
	v_mul_f32_e32 v225, v77, v144
	v_mul_f32_e32 v226, v78, v144
	v_mul_f32_e32 v227, v79, v144
	v_fma_f32 v224, v20, v224, v16
	v_fma_f32 v225, v21, v225, v17
	v_fma_f32 v226, v22, v226, v18
; __device__ __forceinline__ unsigned cvt_pk_bf16(float lo, float hi) { unsigned r; asm volatile("v_cvt_pk_bf16_f32 %0, %1, %2" : "=v"(r) : "v"(lo), "v"(hi)); return r; }
; template <int W>
; __device__ __forceinline__ void pool_chunk(const float* x, bf16_t* P, const LAS float* rs  , const f32x4 gs, const f32x4 sh, size_t r0, bool has_halo, int tid) {
;     ...
;         for (int jj = 0; jj < 16; ++jj) { const int i = i0 + jj; constexpr int dummy = 0; (void)dummy;
;             const int slot = (W - 1 + jj) % W;
;             const f32x4 h = xv[jj] * rs[i + 15] * gs + sh;
;             s += h - ring[slot]; ring[slot] = h;
;             const float inv = has_halo ? (1.0f / W) : (1.0f / (float)((i + 1) < W ? (i + 1) : W));
;             const f32x4 o = s * inv - h;
;             u32x2 w; w.x = cvt_pk_bf16(o[0], o[1]); w.y = cvt_pk_bf16(o[2], o[3]);
;             *(u32x2*)(P + img_off((int)(r0 + i), tid * 4, D)) = w; }
	v_fma_f32 v227, v23, v227, v19
	v_sub_f32_e32 v228, v224, v172
	v_sub_f32_e32 v229, v225, v173
	v_sub_f32_e32 v230, v226, v174
	v_sub_f32_e32 v231, v227, v175
	v_add_f32_e32 v220, v220, v228
	v_add_f32_e32 v221, v221, v229
	v_add_f32_e32 v222, v222, v230
	v_add_f32_e32 v223, v223, v231
	v_mov_b32_e32 v172, v224
	v_mov_b32_e32 v173, v225
	v_mov_b32_e32 v174, v226
	v_mov_b32_e32 v175, v227
	s_cmp_lg_u32 s41, 0
	s_cselect_b32 s57, 0x3e4ccccd, s55
	v_fma_f32 v228, v220, s57, -v224
	v_fma_f32 v229, v221, s57, -v225
	v_fma_f32 v230, v222, s57, -v226
	v_fma_f32 v231, v223, s57, -v227
	v_cvt_pk_bf16_f32 v56, v228, v229
	v_cvt_pk_bf16_f32 v57, v230, v231
	s_mov_b64 exec, s[38:39]
	global_store_dwordx2 v44, v[56:57], s[36:37] offset:256
	s_mov_b64 exec, -1
	v_mul_f32_e32 v224, v80, v145
	v_mul_f32_e32 v225, v81, v145
	v_mul_f32_e32 v226, v82, v145
	v_mul_f32_e32 v227, v83, v145
	v_fma_f32 v224, v20, v224, v16
	v_fma_f32 v225, v21, v225, v17
	v_fma_f32 v226, v22, v226, v18
	v_fma_f32 v227, v23, v227, v19
	v_sub_f32_e32 v228, v224, v176
	v_sub_f32_e32 v229, v225, v177
	v_sub_f32_e32 v230, v226, v178
	v_sub_f32_e32 v231, v227, v179
	v_add_f32_e32 v220, v220, v228
	v_add_f32_e32 v221, v221, v229
	v_add_f32_e32 v222, v222, v230
	v_add_f32_e32 v223, v223, v231
	v_mov_b32_e32 v176, v224
	v_mov_b32_e32 v177, v225
	v_mov_b32_e32 v178, v226
	v_mov_b32_e32 v179, v227
	s_cmp_lg_u32 s41, 0
	s_cselect_b32 s57, 0x3e2aaaab, s55
	v_fma_f32 v228, v220, s57, -v224
	v_fma_f32 v229, v221, s57, -v225
	v_fma_f32 v230, v222, s57, -v226
	v_fma_f32 v231, v223, s57, -v227
	v_cvt_pk_bf16_f32 v232, v228, v229
	v_cvt_pk_bf16_f32 v233, v230, v231
	s_mov_b64 exec, s[38:39]
	global_store_dwordx2 v44, v[232:233], s[36:37] offset:320
	s_mov_b64 exec, -1
	v_mul_f32_e32 v224, v84, v146
	v_mul_f32_e32 v225, v85, v146
	v_mul_f32_e32 v226, v86, v146
	v_mul_f32_e32 v227, v87, v146
	v_fma_f32 v224, v20, v224, v16
	v_fma_f32 v225, v21, v225, v17
	v_fma_f32 v226, v22, v226, v18
	v_fma_f32 v227, v23, v227, v19
	v_sub_f32_e32 v228, v224, v180
	v_sub_f32_e32 v229, v225, v181
	v_sub_f32_e32 v230, v226, v182
	v_sub_f32_e32 v231, v227, v183
	v_add_f32_e32 v220, v220, v228
	v_add_f32_e32 v221, v221, v229
	v_add_f32_e32 v222, v222, v230
	v_add_f32_e32 v223, v223, v231
	v_mov_b32_e32 v180, v224
	v_mov_b32_e32 v181, v225
	v_mov_b32_e32 v182, v226
	v_mov_b32_e32 v183, v227
	s_cmp_lg_u32 s41, 0
	s_cselect_b32 s57, 0x3e124925, s55
	v_fma_f32 v228, v220, s57, -v224
	v_fma_f32 v229, v221, s57, -v225
	v_fma_f32 v230, v222, s57, -v226
	v_fma_f32 v231, v223, s57, -v227
	v_cvt_pk_bf16_f32 v56, v228, v229
	v_cvt_pk_bf16_f32 v57, v230, v231
	s_mov_b64 exec, s[38:39]
	global_store_dwordx2 v44, v[56:57], s[36:37] offset:384
	s_mov_b64 exec, -1
	v_mul_f32_e32 v224, v88, v147
	v_mul_f32_e32 v225, v89, v147
	v_mul_f32_e32 v226, v90, v147
	v_mul_f32_e32 v227, v91, v147
	v_fma_f32 v224, v20, v224, v16
	v_fma_f32 v225, v21, v225, v17
	v_fma_f32 v226, v22, v226, v18
	v_fma_f32 v227, v23, v227, v19
	v_sub_f32_e32 v228, v224, v184
	v_sub_f32_e32 v229, v225, v185
	v_sub_f32_e32 v230, v226, v186
	v_sub_f32_e32 v231, v227, v187
	v_add_f32_e32 v220, v220, v228
	v_add_f32_e32 v221, v221, v229
	v_add_f32_e32 v222, v222, v230
	v_add_f32_e32 v223, v223, v231
	v_mov_b32_e32 v184, v224
	v_mov_b32_e32 v185, v225
	v_mov_b32_e32 v186, v226
	v_mov_b32_e32 v187, v227
	v_fma_f32 v228, v220, s55, -v224
	v_fma_f32 v229, v221, s55, -v225
	v_fma_f32 v230, v222, s55, -v226
	v_fma_f32 v231, v223, s55, -v227
	v_cvt_pk_bf16_f32 v232, v228, v229
	v_cvt_pk_bf16_f32 v233, v230, v231
	s_mov_b64 exec, s[38:39]
	global_store_dwordx2 v44, v[232:233], s[36:37] offset:448
	s_mov_b64 exec, -1
	v_mul_f32_e32 v224, v92, v148
	v_mul_f32_e32 v225, v93, v148
	v_mul_f32_e32 v226, v94, v148
	v_mul_f32_e32 v227, v95, v148
	v_fma_f32 v224, v20, v224, v16
	v_fma_f32 v225, v21, v225, v17
	v_fma_f32 v226, v22, v226, v18
	v_fma_f32 v227, v23, v227, v19
	v_sub_f32_e32 v228, v224, v156
	v_sub_f32_e32 v229, v225, v157
	v_sub_f32_e32 v230, v226, v158
	v_sub_f32_e32 v231, v227, v159
	v_add_f32_e32 v220, v220, v228
	v_add_f32_e32 v221, v221, v229
	v_add_f32_e32 v222, v222, v230
	v_add_f32_e32 v223, v223, v231
	v_mov_b32_e32 v156, v224
	v_mov_b32_e32 v157, v225
	v_mov_b32_e32 v158, v226
	v_mov_b32_e32 v159, v227
	v_fma_f32 v228, v220, s55, -v224
	v_fma_f32 v229, v221, s55, -v225
	v_fma_f32 v230, v222, s55, -v226
	v_fma_f32 v231, v223, s55, -v227
	v_cvt_pk_bf16_f32 v56, v228, v229
	v_cvt_pk_bf16_f32 v57, v230, v231
	s_mov_b64 exec, s[38:39]
	global_store_dwordx2 v45, v[56:57], s[36:37] offset:512
	s_mov_b64 exec, -1
	v_mul_f32_e32 v224, v96, v149
	v_mul_f32_e32 v225, v97, v149
	v_mul_f32_e32 v226, v98, v149
	v_mul_f32_e32 v227, v99, v149
	v_fma_f32 v224, v20, v224, v16
	v_fma_f32 v225, v21, v225, v17
	v_fma_f32 v226, v22, v226, v18
	v_fma_f32 v227, v23, v227, v19
	v_sub_f32_e32 v228, v224, v160
	v_sub_f32_e32 v229, v225, v161
	v_sub_f32_e32 v230, v226, v162
	v_sub_f32_e32 v231, v227, v163
	v_add_f32_e32 v220, v220, v228
	v_add_f32_e32 v221, v221, v229
	v_add_f32_e32 v222, v222, v230
	v_add_f32_e32 v223, v223, v231
	v_mov_b32_e32 v160, v224
	v_mov_b32_e32 v161, v225
	v_mov_b32_e32 v162, v226
	v_mov_b32_e32 v163, v227
	v_fma_f32 v228, v220, s55, -v224
	v_fma_f32 v229, v221, s55, -v225
	v_fma_f32 v230, v222, s55, -v226
	v_fma_f32 v231, v223, s55, -v227
	v_cvt_pk_bf16_f32 v232, v228, v229
	v_cvt_pk_bf16_f32 v233, v230, v231
	s_mov_b64 exec, s[38:39]
	global_store_dwordx2 v45, v[232:233], s[36:37] offset:576
	s_mov_b64 exec, -1
	v_mul_f32_e32 v224, v100, v150
	v_mul_f32_e32 v225, v101, v150
	v_mul_f32_e32 v226, v102, v150
	v_mul_f32_e32 v227, v103, v150
	v_fma_f32 v224, v20, v224, v16
; __device__ __forceinline__ unsigned cvt_pk_bf16(float lo, float hi) { unsigned r; asm volatile("v_cvt_pk_bf16_f32 %0, %1, %2" : "=v"(r) : "v"(lo), "v"(hi)); return r; }
; template <int W>
; __device__ __forceinline__ void pool_chunk(const float* x, bf16_t* P, const LAS float* rs  , const f32x4 gs, const f32x4 sh, size_t r0, bool has_halo, int tid) {
;     ...
;         for (int jj = 0; jj < 16; ++jj) { const int i = i0 + jj; constexpr int dummy = 0; (void)dummy;
;             const int slot = (W - 1 + jj) % W;
;             const f32x4 h = xv[jj] * rs[i + 15] * gs + sh;
;             s += h - ring[slot]; ring[slot] = h;
;             const float inv = has_halo ? (1.0f / W) : (1.0f / (float)((i + 1) < W ? (i + 1) : W));
;             const f32x4 o = s * inv - h;
;             u32x2 w; w.x = cvt_pk_bf16(o[0], o[1]); w.y = cvt_pk_bf16(o[2], o[3]);
;             *(u32x2*)(P + img_off((int)(r0 + i), tid * 4, D)) = w; }
	v_fma_f32 v225, v21, v225, v17
	v_fma_f32 v226, v22, v226, v18
	v_fma_f32 v227, v23, v227, v19
	v_sub_f32_e32 v228, v224, v164
	v_sub_f32_e32 v229, v225, v165
	v_sub_f32_e32 v230, v226, v166
	v_sub_f32_e32 v231, v227, v167
	v_add_f32_e32 v220, v220, v228
	v_add_f32_e32 v221, v221, v229
	v_add_f32_e32 v222, v222, v230
	v_add_f32_e32 v223, v223, v231
	v_mov_b32_e32 v164, v224
	v_mov_b32_e32 v165, v225
	v_mov_b32_e32 v166, v226
	v_mov_b32_e32 v167, v227
	v_fma_f32 v228, v220, s55, -v224
	v_fma_f32 v229, v221, s55, -v225
	v_fma_f32 v230, v222, s55, -v226
	v_fma_f32 v231, v223, s55, -v227
	v_cvt_pk_bf16_f32 v56, v228, v229
	v_cvt_pk_bf16_f32 v57, v230, v231
	s_mov_b64 exec, s[38:39]
	global_store_dwordx2 v45, v[56:57], s[36:37] offset:640
	s_mov_b64 exec, -1
	v_mul_f32_e32 v224, v104, v151
	v_mul_f32_e32 v225, v105, v151
	v_mul_f32_e32 v226, v106, v151
	v_mul_f32_e32 v227, v107, v151
	v_fma_f32 v224, v20, v224, v16
	v_fma_f32 v225, v21, v225, v17
	v_fma_f32 v226, v22, v226, v18
	v_fma_f32 v227, v23, v227, v19
	v_sub_f32_e32 v228, v224, v168
	v_sub_f32_e32 v229, v225, v169
	v_sub_f32_e32 v230, v226, v170
	v_sub_f32_e32 v231, v227, v171
	v_add_f32_e32 v220, v220, v228
	v_add_f32_e32 v221, v221, v229
	v_add_f32_e32 v222, v222, v230
	v_add_f32_e32 v223, v223, v231
	v_mov_b32_e32 v168, v224
	v_mov_b32_e32 v169, v225
	v_mov_b32_e32 v170, v226
	v_mov_b32_e32 v171, v227
	v_fma_f32 v228, v220, s55, -v224
	v_fma_f32 v229, v221, s55, -v225
	v_fma_f32 v230, v222, s55, -v226
	v_fma_f32 v231, v223, s55, -v227
	v_cvt_pk_bf16_f32 v232, v228, v229
	v_cvt_pk_bf16_f32 v233, v230, v231
	s_mov_b64 exec, s[38:39]
	global_store_dwordx2 v45, v[232:233], s[36:37] offset:704
	s_mov_b64 exec, -1
	v_mul_f32_e32 v224, v108, v152
	v_mul_f32_e32 v225, v109, v152
	v_mul_f32_e32 v226, v110, v152
	v_mul_f32_e32 v227, v111, v152
	v_fma_f32 v224, v20, v224, v16
	v_fma_f32 v225, v21, v225, v17
	v_fma_f32 v226, v22, v226, v18
	v_fma_f32 v227, v23, v227, v19
	v_sub_f32_e32 v228, v224, v172
	v_sub_f32_e32 v229, v225, v173
	v_sub_f32_e32 v230, v226, v174
	v_sub_f32_e32 v231, v227, v175
	v_add_f32_e32 v220, v220, v228
	v_add_f32_e32 v221, v221, v229
	v_add_f32_e32 v222, v222, v230
	v_add_f32_e32 v223, v223, v231
	v_mov_b32_e32 v172, v224
	v_mov_b32_e32 v173, v225
	v_mov_b32_e32 v174, v226
	v_mov_b32_e32 v175, v227
	v_fma_f32 v228, v220, s55, -v224
	v_fma_f32 v229, v221, s55, -v225
	v_fma_f32 v230, v222, s55, -v226
	v_fma_f32 v231, v223, s55, -v227
	v_cvt_pk_bf16_f32 v56, v228, v229
	v_cvt_pk_bf16_f32 v57, v230, v231
	s_mov_b64 exec, s[38:39]
	global_store_dwordx2 v45, v[56:57], s[36:37] offset:768
	s_mov_b64 exec, -1
	v_mul_f32_e32 v224, v112, v153
	v_mul_f32_e32 v225, v113, v153
	v_mul_f32_e32 v226, v114, v153
	v_mul_f32_e32 v227, v115, v153
	v_fma_f32 v224, v20, v224, v16
	v_fma_f32 v225, v21, v225, v17
	v_fma_f32 v226, v22, v226, v18
	v_fma_f32 v227, v23, v227, v19
	v_sub_f32_e32 v228, v224, v176
	v_sub_f32_e32 v229, v225, v177
	v_sub_f32_e32 v230, v226, v178
	v_sub_f32_e32 v231, v227, v179
	v_add_f32_e32 v220, v220, v228
	v_add_f32_e32 v221, v221, v229
	v_add_f32_e32 v222, v222, v230
	v_add_f32_e32 v223, v223, v231
	v_mov_b32_e32 v176, v224
	v_mov_b32_e32 v177, v225
	v_mov_b32_e32 v178, v226
	v_mov_b32_e32 v179, v227
	v_fma_f32 v228, v220, s55, -v224
	v_fma_f32 v229, v221, s55, -v225
	v_fma_f32 v230, v222, s55, -v226
	v_fma_f32 v231, v223, s55, -v227
	v_cvt_pk_bf16_f32 v232, v228, v229
	v_cvt_pk_bf16_f32 v233, v230, v231
	s_mov_b64 exec, s[38:39]
	global_store_dwordx2 v45, v[232:233], s[36:37] offset:832
	s_mov_b64 exec, -1
	v_mul_f32_e32 v224, v116, v154
	v_mul_f32_e32 v225, v117, v154
	v_mul_f32_e32 v226, v118, v154
	v_mul_f32_e32 v227, v119, v154
	v_fma_f32 v224, v20, v224, v16
	v_fma_f32 v225, v21, v225, v17
	v_fma_f32 v226, v22, v226, v18
	v_fma_f32 v227, v23, v227, v19
	v_sub_f32_e32 v228, v224, v180
	v_sub_f32_e32 v229, v225, v181
	v_sub_f32_e32 v230, v226, v182
	v_sub_f32_e32 v231, v227, v183
	v_add_f32_e32 v220, v220, v228
	v_add_f32_e32 v221, v221, v229
	v_add_f32_e32 v222, v222, v230
	v_add_f32_e32 v223, v223, v231
	v_mov_b32_e32 v180, v224
	v_mov_b32_e32 v181, v225
	v_mov_b32_e32 v182, v226
	v_mov_b32_e32 v183, v227
	v_fma_f32 v228, v220, s55, -v224
	v_fma_f32 v229, v221, s55, -v225
	v_fma_f32 v230, v222, s55, -v226
	v_fma_f32 v231, v223, s55, -v227
	v_cvt_pk_bf16_f32 v56, v228, v229
	v_cvt_pk_bf16_f32 v57, v230, v231
	s_mov_b64 exec, s[38:39]
	global_store_dwordx2 v45, v[56:57], s[36:37] offset:896
	s_mov_b64 exec, -1
	v_mul_f32_e32 v224, v120, v155
	v_mul_f32_e32 v225, v121, v155
	v_mul_f32_e32 v226, v122, v155
	v_mul_f32_e32 v227, v123, v155
	v_fma_f32 v224, v20, v224, v16
	v_fma_f32 v225, v21, v225, v17
	v_fma_f32 v226, v22, v226, v18
	v_fma_f32 v227, v23, v227, v19
	v_sub_f32_e32 v228, v224, v184
	v_sub_f32_e32 v229, v225, v185
	v_sub_f32_e32 v230, v226, v186
	v_sub_f32_e32 v231, v227, v187
	v_add_f32_e32 v220, v220, v228
	v_add_f32_e32 v221, v221, v229
	v_add_f32_e32 v222, v222, v230
	v_add_f32_e32 v223, v223, v231
	v_mov_b32_e32 v184, v224
	v_mov_b32_e32 v185, v225
	v_mov_b32_e32 v186, v226
	v_mov_b32_e32 v187, v227
	v_fma_f32 v228, v220, s55, -v224
	v_fma_f32 v229, v221, s55, -v225
	v_fma_f32 v230, v222, s55, -v226
	v_fma_f32 v231, v223, s55, -v227
	v_cvt_pk_bf16_f32 v232, v228, v229
	v_cvt_pk_bf16_f32 v233, v230, v231
	s_mov_b64 exec, s[38:39]
	global_store_dwordx2 v45, v[232:233], s[36:37] offset:960
	s_mov_b64 exec, -1
	s_branch .Lp1_join
; __device__ __forceinline__ unsigned cvt_pk_bf16(float lo, float hi) { unsigned r; asm volatile("v_cvt_pk_bf16_f32 %0, %1, %2" : "=v"(r) : "v"(lo), "v"(hi)); return r; }
; template <int W>
; __device__ __forceinline__ void pool_chunk(const float* x, bf16_t* P, const LAS float* rs  , const f32x4 gs, const f32x4 sh, size_t r0, bool has_halo, int tid) {
;     ...
;         for (int jj = 0; jj < 16; ++jj) { const int i = i0 + jj; constexpr int dummy = 0; (void)dummy;
;             const int slot = (W - 1 + jj) % W;
;             const f32x4 h = xv[jj] * rs[i + 15] * gs + sh;
;             s += h - ring[slot]; ring[slot] = h;
;             const float inv = has_halo ? (1.0f / W) : (1.0f / (float)((i + 1) < W ? (i + 1) : W));
;             const f32x4 o = s * inv - h;
;             u32x2 w; w.x = cvt_pk_bf16(o[0], o[1]); w.y = cvt_pk_bf16(o[2], o[3]);
;             *(u32x2*)(P + img_off((int)(r0 + i), tid * 4, D)) = w; }
.Lp1_w4:
	s_mov_b32 s55, 0x3e800000
	v_mul_f32_e32 v224, v60, v140
	v_mul_f32_e32 v225, v61, v140
	v_mul_f32_e32 v226, v62, v140
	v_mul_f32_e32 v227, v63, v140
	v_fma_f32 v224, v20, v224, v16
	v_fma_f32 v225, v21, v225, v17
	v_fma_f32 v226, v22, v226, v18
	v_fma_f32 v227, v23, v227, v19
	v_sub_f32_e32 v228, v224, v156
	v_sub_f32_e32 v229, v225, v157
	v_sub_f32_e32 v230, v226, v158
	v_sub_f32_e32 v231, v227, v159
	v_add_f32_e32 v220, v220, v228
	v_add_f32_e32 v221, v221, v229
	v_add_f32_e32 v222, v222, v230
	v_add_f32_e32 v223, v223, v231
	v_mov_b32_e32 v156, v224
	v_mov_b32_e32 v157, v225
	v_mov_b32_e32 v158, v226
	v_mov_b32_e32 v159, v227
	s_cmp_lg_u32 s41, 0
	s_cselect_b32 s57, 0x3f800000, s55
	v_fma_f32 v228, v220, s57, -v224
	v_fma_f32 v229, v221, s57, -v225
	v_fma_f32 v230, v222, s57, -v226
	v_fma_f32 v231, v223, s57, -v227
	v_cvt_pk_bf16_f32 v56, v228, v229
	v_cvt_pk_bf16_f32 v57, v230, v231
	s_mov_b64 exec, s[38:39]
	global_store_dwordx2 v44, v[56:57], s[36:37] offset:0
	s_mov_b64 exec, -1
	v_mul_f32_e32 v224, v64, v141
	v_mul_f32_e32 v225, v65, v141
	v_mul_f32_e32 v226, v66, v141
	v_mul_f32_e32 v227, v67, v141
	v_fma_f32 v224, v20, v224, v16
	v_fma_f32 v225, v21, v225, v17
	v_fma_f32 v226, v22, v226, v18
	v_fma_f32 v227, v23, v227, v19
	v_sub_f32_e32 v228, v224, v160
	v_sub_f32_e32 v229, v225, v161
	v_sub_f32_e32 v230, v226, v162
	v_sub_f32_e32 v231, v227, v163
	v_add_f32_e32 v220, v220, v228
	v_add_f32_e32 v221, v221, v229
	v_add_f32_e32 v222, v222, v230
	v_add_f32_e32 v223, v223, v231
	v_mov_b32_e32 v160, v224
	v_mov_b32_e32 v161, v225
	v_mov_b32_e32 v162, v226
	v_mov_b32_e32 v163, v227
	s_cmp_lg_u32 s41, 0
	s_cselect_b32 s57, 0x3f000000, s55
	v_fma_f32 v228, v220, s57, -v224
	v_fma_f32 v229, v221, s57, -v225
	v_fma_f32 v230, v222, s57, -v226
	v_fma_f32 v231, v223, s57, -v227
	v_cvt_pk_bf16_f32 v232, v228, v229
	v_cvt_pk_bf16_f32 v233, v230, v231
	s_mov_b64 exec, s[38:39]
	global_store_dwordx2 v44, v[232:233], s[36:37] offset:64
	s_mov_b64 exec, -1
	v_mul_f32_e32 v224, v68, v142
	v_mul_f32_e32 v225, v69, v142
	v_mul_f32_e32 v226, v70, v142
	v_mul_f32_e32 v227, v71, v142
	v_fma_f32 v224, v20, v224, v16
	v_fma_f32 v225, v21, v225, v17
	v_fma_f32 v226, v22, v226, v18
	v_fma_f32 v227, v23, v227, v19
	v_sub_f32_e32 v228, v224, v164
	v_sub_f32_e32 v229, v225, v165
	v_sub_f32_e32 v230, v226, v166
	v_sub_f32_e32 v231, v227, v167
	v_add_f32_e32 v220, v220, v228
	v_add_f32_e32 v221, v221, v229
	v_add_f32_e32 v222, v222, v230
	v_add_f32_e32 v223, v223, v231
	v_mov_b32_e32 v164, v224
	v_mov_b32_e32 v165, v225
	v_mov_b32_e32 v166, v226
	v_mov_b32_e32 v167, v227
	s_cmp_lg_u32 s41, 0
	s_cselect_b32 s57, 0x3eaaaaab, s55
	v_fma_f32 v228, v220, s57, -v224
	v_fma_f32 v229, v221, s57, -v225
	v_fma_f32 v230, v222, s57, -v226
	v_fma_f32 v231, v223, s57, -v227
	v_cvt_pk_bf16_f32 v56, v228, v229
	v_cvt_pk_bf16_f32 v57, v230, v231
	s_mov_b64 exec, s[38:39]
	global_store_dwordx2 v44, v[56:57], s[36:37] offset:128
	s_mov_b64 exec, -1
	v_mul_f32_e32 v224, v72, v143
	v_mul_f32_e32 v225, v73, v143
	v_mul_f32_e32 v226, v74, v143
	v_mul_f32_e32 v227, v75, v143
	v_fma_f32 v224, v20, v224, v16
	v_fma_f32 v225, v21, v225, v17
	v_fma_f32 v226, v22, v226, v18
	v_fma_f32 v227, v23, v227, v19
	v_sub_f32_e32 v228, v224, v168
	v_sub_f32_e32 v229, v225, v169
	v_sub_f32_e32 v230, v226, v170
	v_sub_f32_e32 v231, v227, v171
	v_add_f32_e32 v220, v220, v228
	v_add_f32_e32 v221, v221, v229
	v_add_f32_e32 v222, v222, v230
	v_add_f32_e32 v223, v223, v231
	v_mov_b32_e32 v168, v224
	v_mov_b32_e32 v169, v225
	v_mov_b32_e32 v170, v226
	v_mov_b32_e32 v171, v227
	v_fma_f32 v228, v220, s55, -v224
	v_fma_f32 v229, v221, s55, -v225
	v_fma_f32 v230, v222, s55, -v226
	v_fma_f32 v231, v223, s55, -v227
	v_cvt_pk_bf16_f32 v232, v228, v229
	v_cvt_pk_bf16_f32 v233, v230, v231
	s_mov_b64 exec, s[38:39]
	global_store_dwordx2 v44, v[232:233], s[36:37] offset:192
	s_mov_b64 exec, -1
	v_mul_f32_e32 v224, v76, v144
	v_mul_f32_e32 v225, v77, v144
	v_mul_f32_e32 v226, v78, v144
	v_mul_f32_e32 v227, v79, v144
	v_fma_f32 v224, v20, v224, v16
	v_fma_f32 v225, v21, v225, v17
	v_fma_f32 v226, v22, v226, v18
	v_fma_f32 v227, v23, v227, v19
	v_sub_f32_e32 v228, v224, v156
	v_sub_f32_e32 v229, v225, v157
	v_sub_f32_e32 v230, v226, v158
	v_sub_f32_e32 v231, v227, v159
	v_add_f32_e32 v220, v220, v228
	v_add_f32_e32 v221, v221, v229
	v_add_f32_e32 v222, v222, v230
	v_add_f32_e32 v223, v223, v231
	v_mov_b32_e32 v156, v224
	v_mov_b32_e32 v157, v225
	v_mov_b32_e32 v158, v226
	v_mov_b32_e32 v159, v227
	v_fma_f32 v228, v220, s55, -v224
	v_fma_f32 v229, v221, s55, -v225
	v_fma_f32 v230, v222, s55, -v226
	v_fma_f32 v231, v223, s55, -v227
	v_cvt_pk_bf16_f32 v56, v228, v229
	v_cvt_pk_bf16_f32 v57, v230, v231
	s_mov_b64 exec, s[38:39]
	global_store_dwordx2 v44, v[56:57], s[36:37] offset:256
	s_mov_b64 exec, -1
	v_mul_f32_e32 v224, v80, v145
	v_mul_f32_e32 v225, v81, v145
	v_mul_f32_e32 v226, v82, v145
	v_mul_f32_e32 v227, v83, v145
	v_fma_f32 v224, v20, v224, v16
	v_fma_f32 v225, v21, v225, v17
	v_fma_f32 v226, v22, v226, v18
	v_fma_f32 v227, v23, v227, v19
	v_sub_f32_e32 v228, v224, v160
	v_sub_f32_e32 v229, v225, v161
	v_sub_f32_e32 v230, v226, v162
	v_sub_f32_e32 v231, v227, v163
	v_add_f32_e32 v220, v220, v228
	v_add_f32_e32 v221, v221, v229
	v_add_f32_e32 v222, v222, v230
	v_add_f32_e32 v223, v223, v231
	v_mov_b32_e32 v160, v224
	v_mov_b32_e32 v161, v225
	v_mov_b32_e32 v162, v226
	v_mov_b32_e32 v163, v227
	v_fma_f32 v228, v220, s55, -v224
	v_fma_f32 v229, v221, s55, -v225
	v_fma_f32 v230, v222, s55, -v226
	v_fma_f32 v231, v223, s55, -v227
	v_cvt_pk_bf16_f32 v232, v228, v229
	v_cvt_pk_bf16_f32 v233, v230, v231
; __device__ __forceinline__ unsigned cvt_pk_bf16(float lo, float hi) { unsigned r; asm volatile("v_cvt_pk_bf16_f32 %0, %1, %2" : "=v"(r) : "v"(lo), "v"(hi)); return r; }
; template <int W>
; __device__ __forceinline__ void pool_chunk(const float* x, bf16_t* P, const LAS float* rs  , const f32x4 gs, const f32x4 sh, size_t r0, bool has_halo, int tid) {
;     ...
;         for (int jj = 0; jj < 16; ++jj) { const int i = i0 + jj; constexpr int dummy = 0; (void)dummy;
;             const int slot = (W - 1 + jj) % W;
;             const f32x4 h = xv[jj] * rs[i + 15] * gs + sh;
;             s += h - ring[slot]; ring[slot] = h;
;             const float inv = has_halo ? (1.0f / W) : (1.0f / (float)((i + 1) < W ? (i + 1) : W));
;             const f32x4 o = s * inv - h;
;             u32x2 w; w.x = cvt_pk_bf16(o[0], o[1]); w.y = cvt_pk_bf16(o[2], o[3]);
;             *(u32x2*)(P + img_off((int)(r0 + i), tid * 4, D)) = w; }
	s_mov_b64 exec, s[38:39]
	global_store_dwordx2 v44, v[232:233], s[36:37] offset:320
	s_mov_b64 exec, -1
	v_mul_f32_e32 v224, v84, v146
	v_mul_f32_e32 v225, v85, v146
	v_mul_f32_e32 v226, v86, v146
	v_mul_f32_e32 v227, v87, v146
	v_fma_f32 v224, v20, v224, v16
	v_fma_f32 v225, v21, v225, v17
	v_fma_f32 v226, v22, v226, v18
	v_fma_f32 v227, v23, v227, v19
	v_sub_f32_e32 v228, v224, v164
	v_sub_f32_e32 v229, v225, v165
	v_sub_f32_e32 v230, v226, v166
	v_sub_f32_e32 v231, v227, v167
	v_add_f32_e32 v220, v220, v228
	v_add_f32_e32 v221, v221, v229
	v_add_f32_e32 v222, v222, v230
	v_add_f32_e32 v223, v223, v231
	v_mov_b32_e32 v164, v224
	v_mov_b32_e32 v165, v225
	v_mov_b32_e32 v166, v226
	v_mov_b32_e32 v167, v227
	v_fma_f32 v228, v220, s55, -v224
	v_fma_f32 v229, v221, s55, -v225
	v_fma_f32 v230, v222, s55, -v226
	v_fma_f32 v231, v223, s55, -v227
	v_cvt_pk_bf16_f32 v56, v228, v229
	v_cvt_pk_bf16_f32 v57, v230, v231
	s_mov_b64 exec, s[38:39]
	global_store_dwordx2 v44, v[56:57], s[36:37] offset:384
	s_mov_b64 exec, -1
	v_mul_f32_e32 v224, v88, v147
	v_mul_f32_e32 v225, v89, v147
	v_mul_f32_e32 v226, v90, v147
	v_mul_f32_e32 v227, v91, v147
	v_fma_f32 v224, v20, v224, v16
	v_fma_f32 v225, v21, v225, v17
	v_fma_f32 v226, v22, v226, v18
	v_fma_f32 v227, v23, v227, v19
	v_sub_f32_e32 v228, v224, v168
	v_sub_f32_e32 v229, v225, v169
	v_sub_f32_e32 v230, v226, v170
	v_sub_f32_e32 v231, v227, v171
	v_add_f32_e32 v220, v220, v228
	v_add_f32_e32 v221, v221, v229
	v_add_f32_e32 v222, v222, v230
	v_add_f32_e32 v223, v223, v231
	v_mov_b32_e32 v168, v224
	v_mov_b32_e32 v169, v225
	v_mov_b32_e32 v170, v226
	v_mov_b32_e32 v171, v227
	v_fma_f32 v228, v220, s55, -v224
	v_fma_f32 v229, v221, s55, -v225
	v_fma_f32 v230, v222, s55, -v226
	v_fma_f32 v231, v223, s55, -v227
	v_cvt_pk_bf16_f32 v232, v228, v229
	v_cvt_pk_bf16_f32 v233, v230, v231
	s_mov_b64 exec, s[38:39]
	global_store_dwordx2 v44, v[232:233], s[36:37] offset:448
	s_mov_b64 exec, -1
	v_mul_f32_e32 v224, v92, v148
	v_mul_f32_e32 v225, v93, v148
	v_mul_f32_e32 v226, v94, v148
	v_mul_f32_e32 v227, v95, v148
	v_fma_f32 v224, v20, v224, v16
	v_fma_f32 v225, v21, v225, v17
	v_fma_f32 v226, v22, v226, v18
	v_fma_f32 v227, v23, v227, v19
	v_sub_f32_e32 v228, v224, v156
	v_sub_f32_e32 v229, v225, v157
	v_sub_f32_e32 v230, v226, v158
	v_sub_f32_e32 v231, v227, v159
	v_add_f32_e32 v220, v220, v228
	v_add_f32_e32 v221, v221, v229
	v_add_f32_e32 v222, v222, v230
	v_add_f32_e32 v223, v223, v231
	v_mov_b32_e32 v156, v224
	v_mov_b32_e32 v157, v225
	v_mov_b32_e32 v158, v226
	v_mov_b32_e32 v159, v227
	v_fma_f32 v228, v220, s55, -v224
	v_fma_f32 v229, v221, s55, -v225
	v_fma_f32 v230, v222, s55, -v226
	v_fma_f32 v231, v223, s55, -v227
	v_cvt_pk_bf16_f32 v56, v228, v229
	v_cvt_pk_bf16_f32 v57, v230, v231
	s_mov_b64 exec, s[38:39]
	global_store_dwordx2 v45, v[56:57], s[36:37] offset:512
	s_mov_b64 exec, -1
	v_mul_f32_e32 v224, v96, v149
	v_mul_f32_e32 v225, v97, v149
	v_mul_f32_e32 v226, v98, v149
	v_mul_f32_e32 v227, v99, v149
	v_fma_f32 v224, v20, v224, v16
	v_fma_f32 v225, v21, v225, v17
	v_fma_f32 v226, v22, v226, v18
	v_fma_f32 v227, v23, v227, v19
	v_sub_f32_e32 v228, v224, v160
	v_sub_f32_e32 v229, v225, v161
	v_sub_f32_e32 v230, v226, v162
	v_sub_f32_e32 v231, v227, v163
	v_add_f32_e32 v220, v220, v228
	v_add_f32_e32 v221, v221, v229
	v_add_f32_e32 v222, v222, v230
	v_add_f32_e32 v223, v223, v231
	v_mov_b32_e32 v160, v224
	v_mov_b32_e32 v161, v225
	v_mov_b32_e32 v162, v226
	v_mov_b32_e32 v163, v227
	v_fma_f32 v228, v220, s55, -v224
	v_fma_f32 v229, v221, s55, -v225
	v_fma_f32 v230, v222, s55, -v226
	v_fma_f32 v231, v223, s55, -v227
	v_cvt_pk_bf16_f32 v232, v228, v229
	v_cvt_pk_bf16_f32 v233, v230, v231
	s_mov_b64 exec, s[38:39]
	global_store_dwordx2 v45, v[232:233], s[36:37] offset:576
	s_mov_b64 exec, -1
	v_mul_f32_e32 v224, v100, v150
	v_mul_f32_e32 v225, v101, v150
	v_mul_f32_e32 v226, v102, v150
	v_mul_f32_e32 v227, v103, v150
	v_fma_f32 v224, v20, v224, v16
	v_fma_f32 v225, v21, v225, v17
	v_fma_f32 v226, v22, v226, v18
	v_fma_f32 v227, v23, v227, v19
	v_sub_f32_e32 v228, v224, v164
	v_sub_f32_e32 v229, v225, v165
	v_sub_f32_e32 v230, v226, v166
	v_sub_f32_e32 v231, v227, v167
	v_add_f32_e32 v220, v220, v228
	v_add_f32_e32 v221, v221, v229
	v_add_f32_e32 v222, v222, v230
	v_add_f32_e32 v223, v223, v231
	v_mov_b32_e32 v164, v224
	v_mov_b32_e32 v165, v225
	v_mov_b32_e32 v166, v226
	v_mov_b32_e32 v167, v227
	v_fma_f32 v228, v220, s55, -v224
	v_fma_f32 v229, v221, s55, -v225
	v_fma_f32 v230, v222, s55, -v226
	v_fma_f32 v231, v223, s55, -v227
	v_cvt_pk_bf16_f32 v56, v228, v229
	v_cvt_pk_bf16_f32 v57, v230, v231
	s_mov_b64 exec, s[38:39]
	global_store_dwordx2 v45, v[56:57], s[36:37] offset:640
	s_mov_b64 exec, -1
	v_mul_f32_e32 v224, v104, v151
	v_mul_f32_e32 v225, v105, v151
	v_mul_f32_e32 v226, v106, v151
	v_mul_f32_e32 v227, v107, v151
	v_fma_f32 v224, v20, v224, v16
	v_fma_f32 v225, v21, v225, v17
	v_fma_f32 v226, v22, v226, v18
	v_fma_f32 v227, v23, v227, v19
	v_sub_f32_e32 v228, v224, v168
	v_sub_f32_e32 v229, v225, v169
	v_sub_f32_e32 v230, v226, v170
	v_sub_f32_e32 v231, v227, v171
	v_add_f32_e32 v220, v220, v228
	v_add_f32_e32 v221, v221, v229
	v_add_f32_e32 v222, v222, v230
	v_add_f32_e32 v223, v223, v231
	v_mov_b32_e32 v168, v224
	v_mov_b32_e32 v169, v225
	v_mov_b32_e32 v170, v226
	v_mov_b32_e32 v171, v227
	v_fma_f32 v228, v220, s55, -v224
	v_fma_f32 v229, v221, s55, -v225
	v_fma_f32 v230, v222, s55, -v226
	v_fma_f32 v231, v223, s55, -v227
	v_cvt_pk_bf16_f32 v232, v228, v229
	v_cvt_pk_bf16_f32 v233, v230, v231
	s_mov_b64 exec, s[38:39]
	global_store_dwordx2 v45, v[232:233], s[36:37] offset:704
; __device__ __forceinline__ unsigned cvt_pk_bf16(float lo, float hi) { unsigned r; asm volatile("v_cvt_pk_bf16_f32 %0, %1, %2" : "=v"(r) : "v"(lo), "v"(hi)); return r; }
; template <int W>
; __device__ __forceinline__ void pool_chunk(const float* x, bf16_t* P, const LAS float* rs  , const f32x4 gs, const f32x4 sh, size_t r0, bool has_halo, int tid) {
;     ...
;         for (int jj = 0; jj < 16; ++jj) { const int i = i0 + jj; constexpr int dummy = 0; (void)dummy;
;             const int slot = (W - 1 + jj) % W;
;             const f32x4 h = xv[jj] * rs[i + 15] * gs + sh;
;             s += h - ring[slot]; ring[slot] = h;
;             const float inv = has_halo ? (1.0f / W) : (1.0f / (float)((i + 1) < W ? (i + 1) : W));
;             const f32x4 o = s * inv - h;
;             u32x2 w; w.x = cvt_pk_bf16(o[0], o[1]); w.y = cvt_pk_bf16(o[2], o[3]);
;             *(u32x2*)(P + img_off((int)(r0 + i), tid * 4, D)) = w; }
	s_mov_b64 exec, -1
	v_mul_f32_e32 v224, v108, v152
	v_mul_f32_e32 v225, v109, v152
	v_mul_f32_e32 v226, v110, v152
	v_mul_f32_e32 v227, v111, v152
	v_fma_f32 v224, v20, v224, v16
	v_fma_f32 v225, v21, v225, v17
	v_fma_f32 v226, v22, v226, v18
	v_fma_f32 v227, v23, v227, v19
	v_sub_f32_e32 v228, v224, v156
	v_sub_f32_e32 v229, v225, v157
	v_sub_f32_e32 v230, v226, v158
	v_sub_f32_e32 v231, v227, v159
	v_add_f32_e32 v220, v220, v228
	v_add_f32_e32 v221, v221, v229
	v_add_f32_e32 v222, v222, v230
	v_add_f32_e32 v223, v223, v231
	v_mov_b32_e32 v156, v224
	v_mov_b32_e32 v157, v225
	v_mov_b32_e32 v158, v226
	v_mov_b32_e32 v159, v227
	v_fma_f32 v228, v220, s55, -v224
	v_fma_f32 v229, v221, s55, -v225
	v_fma_f32 v230, v222, s55, -v226
	v_fma_f32 v231, v223, s55, -v227
	v_cvt_pk_bf16_f32 v56, v228, v229
	v_cvt_pk_bf16_f32 v57, v230, v231
	s_mov_b64 exec, s[38:39]
	global_store_dwordx2 v45, v[56:57], s[36:37] offset:768
	s_mov_b64 exec, -1
	v_mul_f32_e32 v224, v112, v153
	v_mul_f32_e32 v225, v113, v153
	v_mul_f32_e32 v226, v114, v153
	v_mul_f32_e32 v227, v115, v153
	v_fma_f32 v224, v20, v224, v16
	v_fma_f32 v225, v21, v225, v17
	v_fma_f32 v226, v22, v226, v18
	v_fma_f32 v227, v23, v227, v19
	v_sub_f32_e32 v228, v224, v160
	v_sub_f32_e32 v229, v225, v161
	v_sub_f32_e32 v230, v226, v162
	v_sub_f32_e32 v231, v227, v163
	v_add_f32_e32 v220, v220, v228
	v_add_f32_e32 v221, v221, v229
	v_add_f32_e32 v222, v222, v230
	v_add_f32_e32 v223, v223, v231
	v_mov_b32_e32 v160, v224
	v_mov_b32_e32 v161, v225
	v_mov_b32_e32 v162, v226
	v_mov_b32_e32 v163, v227
	v_fma_f32 v228, v220, s55, -v224
	v_fma_f32 v229, v221, s55, -v225
	v_fma_f32 v230, v222, s55, -v226
	v_fma_f32 v231, v223, s55, -v227
	v_cvt_pk_bf16_f32 v232, v228, v229
	v_cvt_pk_bf16_f32 v233, v230, v231
	s_mov_b64 exec, s[38:39]
	global_store_dwordx2 v45, v[232:233], s[36:37] offset:832
	s_mov_b64 exec, -1
	v_mul_f32_e32 v224, v116, v154
	v_mul_f32_e32 v225, v117, v154
	v_mul_f32_e32 v226, v118, v154
	v_mul_f32_e32 v227, v119, v154
	v_fma_f32 v224, v20, v224, v16
	v_fma_f32 v225, v21, v225, v17
	v_fma_f32 v226, v22, v226, v18
	v_fma_f32 v227, v23, v227, v19
	v_sub_f32_e32 v228, v224, v164
	v_sub_f32_e32 v229, v225, v165
	v_sub_f32_e32 v230, v226, v166
	v_sub_f32_e32 v231, v227, v167
	v_add_f32_e32 v220, v220, v228
	v_add_f32_e32 v221, v221, v229
	v_add_f32_e32 v222, v222, v230
	v_add_f32_e32 v223, v223, v231
	v_mov_b32_e32 v164, v224
	v_mov_b32_e32 v165, v225
	v_mov_b32_e32 v166, v226
	v_mov_b32_e32 v167, v227
	v_fma_f32 v228, v220, s55, -v224
	v_fma_f32 v229, v221, s55, -v225
	v_fma_f32 v230, v222, s55, -v226
	v_fma_f32 v231, v223, s55, -v227
	v_cvt_pk_bf16_f32 v56, v228, v229
	v_cvt_pk_bf16_f32 v57, v230, v231
	s_mov_b64 exec, s[38:39]
	global_store_dwordx2 v45, v[56:57], s[36:37] offset:896
	s_mov_b64 exec, -1
	v_mul_f32_e32 v224, v120, v155
	v_mul_f32_e32 v225, v121, v155
	v_mul_f32_e32 v226, v122, v155
	v_mul_f32_e32 v227, v123, v155
	v_fma_f32 v224, v20, v224, v16
	v_fma_f32 v225, v21, v225, v17
	v_fma_f32 v226, v22, v226, v18
	v_fma_f32 v227, v23, v227, v19
	v_sub_f32_e32 v228, v224, v168
	v_sub_f32_e32 v229, v225, v169
	v_sub_f32_e32 v230, v226, v170
	v_sub_f32_e32 v231, v227, v171
	v_add_f32_e32 v220, v220, v228
	v_add_f32_e32 v221, v221, v229
	v_add_f32_e32 v222, v222, v230
	v_add_f32_e32 v223, v223, v231
	v_mov_b32_e32 v168, v224
	v_mov_b32_e32 v169, v225
	v_mov_b32_e32 v170, v226
	v_mov_b32_e32 v171, v227
	v_fma_f32 v228, v220, s55, -v224
	v_fma_f32 v229, v221, s55, -v225
	v_fma_f32 v230, v222, s55, -v226
	v_fma_f32 v231, v223, s55, -v227
	v_cvt_pk_bf16_f32 v232, v228, v229
	v_cvt_pk_bf16_f32 v233, v230, v231
	s_mov_b64 exec, s[38:39]
	global_store_dwordx2 v45, v[232:233], s[36:37] offset:960
	s_mov_b64 exec, -1
	s_branch .Lp1_join
.Lp1_w2:
	s_mov_b32 s55, 0x3f000000
	v_mul_f32_e32 v224, v60, v140
	v_mul_f32_e32 v225, v61, v140
	v_mul_f32_e32 v226, v62, v140
	v_mul_f32_e32 v227, v63, v140
	v_fma_f32 v224, v20, v224, v16
	v_fma_f32 v225, v21, v225, v17
	v_fma_f32 v226, v22, v226, v18
	v_fma_f32 v227, v23, v227, v19
	v_sub_f32_e32 v228, v224, v156
	v_sub_f32_e32 v229, v225, v157
	v_sub_f32_e32 v230, v226, v158
	v_sub_f32_e32 v231, v227, v159
	v_add_f32_e32 v220, v220, v228
	v_add_f32_e32 v221, v221, v229
	v_add_f32_e32 v222, v222, v230
	v_add_f32_e32 v223, v223, v231
	v_mov_b32_e32 v156, v224
	v_mov_b32_e32 v157, v225
	v_mov_b32_e32 v158, v226
	v_mov_b32_e32 v159, v227
	s_cmp_lg_u32 s41, 0
	s_cselect_b32 s57, 0x3f800000, s55
	v_fma_f32 v228, v220, s57, -v224
	v_fma_f32 v229, v221, s57, -v225
	v_fma_f32 v230, v222, s57, -v226
	v_fma_f32 v231, v223, s57, -v227
	v_cvt_pk_bf16_f32 v56, v228, v229
	v_cvt_pk_bf16_f32 v57, v230, v231
	s_mov_b64 exec, s[38:39]
	global_store_dwordx2 v44, v[56:57], s[36:37] offset:0
	s_mov_b64 exec, -1
	v_mul_f32_e32 v224, v64, v141
	v_mul_f32_e32 v225, v65, v141
	v_mul_f32_e32 v226, v66, v141
	v_mul_f32_e32 v227, v67, v141
	v_fma_f32 v224, v20, v224, v16
	v_fma_f32 v225, v21, v225, v17
	v_fma_f32 v226, v22, v226, v18
	v_fma_f32 v227, v23, v227, v19
	v_sub_f32_e32 v228, v224, v160
	v_sub_f32_e32 v229, v225, v161
	v_sub_f32_e32 v230, v226, v162
	v_sub_f32_e32 v231, v227, v163
	v_add_f32_e32 v220, v220, v228
	v_add_f32_e32 v221, v221, v229
	v_add_f32_e32 v222, v222, v230
	v_add_f32_e32 v223, v223, v231
	v_mov_b32_e32 v160, v224
	v_mov_b32_e32 v161, v225
	v_mov_b32_e32 v162, v226
	v_mov_b32_e32 v163, v227
	v_fma_f32 v228, v220, s55, -v224
	v_fma_f32 v229, v221, s55, -v225
	v_fma_f32 v230, v222, s55, -v226
	v_fma_f32 v231, v223, s55, -v227
	v_cvt_pk_bf16_f32 v232, v228, v229
	v_cvt_pk_bf16_f32 v233, v230, v231
	s_mov_b64 exec, s[38:39]
	global_store_dwordx2 v44, v[232:233], s[36:37] offset:64
; __device__ __forceinline__ unsigned cvt_pk_bf16(float lo, float hi) { unsigned r; asm volatile("v_cvt_pk_bf16_f32 %0, %1, %2" : "=v"(r) : "v"(lo), "v"(hi)); return r; }
; template <int W>
; __device__ __forceinline__ void pool_chunk(const float* x, bf16_t* P, const LAS float* rs  , const f32x4 gs, const f32x4 sh, size_t r0, bool has_halo, int tid) {
;     ...
;         for (int jj = 0; jj < 16; ++jj) { const int i = i0 + jj; constexpr int dummy = 0; (void)dummy;
;             const int slot = (W - 1 + jj) % W;
;             const f32x4 h = xv[jj] * rs[i + 15] * gs + sh;
;             s += h - ring[slot]; ring[slot] = h;
;             const float inv = has_halo ? (1.0f / W) : (1.0f / (float)((i + 1) < W ? (i + 1) : W));
;             const f32x4 o = s * inv - h;
;             u32x2 w; w.x = cvt_pk_bf16(o[0], o[1]); w.y = cvt_pk_bf16(o[2], o[3]);
;             *(u32x2*)(P + img_off((int)(r0 + i), tid * 4, D)) = w; }
	s_mov_b64 exec, -1
	v_mul_f32_e32 v224, v68, v142
	v_mul_f32_e32 v225, v69, v142
	v_mul_f32_e32 v226, v70, v142
	v_mul_f32_e32 v227, v71, v142
	v_fma_f32 v224, v20, v224, v16
	v_fma_f32 v225, v21, v225, v17
	v_fma_f32 v226, v22, v226, v18
	v_fma_f32 v227, v23, v227, v19
	v_sub_f32_e32 v228, v224, v156
	v_sub_f32_e32 v229, v225, v157
	v_sub_f32_e32 v230, v226, v158
	v_sub_f32_e32 v231, v227, v159
	v_add_f32_e32 v220, v220, v228
	v_add_f32_e32 v221, v221, v229
	v_add_f32_e32 v222, v222, v230
	v_add_f32_e32 v223, v223, v231
	v_mov_b32_e32 v156, v224
	v_mov_b32_e32 v157, v225
	v_mov_b32_e32 v158, v226
	v_mov_b32_e32 v159, v227
	v_fma_f32 v228, v220, s55, -v224
	v_fma_f32 v229, v221, s55, -v225
	v_fma_f32 v230, v222, s55, -v226
	v_fma_f32 v231, v223, s55, -v227
	v_cvt_pk_bf16_f32 v56, v228, v229
	v_cvt_pk_bf16_f32 v57, v230, v231
	s_mov_b64 exec, s[38:39]
	global_store_dwordx2 v44, v[56:57], s[36:37] offset:128
	s_mov_b64 exec, -1
	v_mul_f32_e32 v224, v72, v143
	v_mul_f32_e32 v225, v73, v143
	v_mul_f32_e32 v226, v74, v143
	v_mul_f32_e32 v227, v75, v143
	v_fma_f32 v224, v20, v224, v16
	v_fma_f32 v225, v21, v225, v17
	v_fma_f32 v226, v22, v226, v18
	v_fma_f32 v227, v23, v227, v19
	v_sub_f32_e32 v228, v224, v160
	v_sub_f32_e32 v229, v225, v161
	v_sub_f32_e32 v230, v226, v162
	v_sub_f32_e32 v231, v227, v163
	v_add_f32_e32 v220, v220, v228
	v_add_f32_e32 v221, v221, v229
	v_add_f32_e32 v222, v222, v230
	v_add_f32_e32 v223, v223, v231
	v_mov_b32_e32 v160, v224
	v_mov_b32_e32 v161, v225
	v_mov_b32_e32 v162, v226
	v_mov_b32_e32 v163, v227
	v_fma_f32 v228, v220, s55, -v224
	v_fma_f32 v229, v221, s55, -v225
	v_fma_f32 v230, v222, s55, -v226
	v_fma_f32 v231, v223, s55, -v227
	v_cvt_pk_bf16_f32 v232, v228, v229
	v_cvt_pk_bf16_f32 v233, v230, v231
	s_mov_b64 exec, s[38:39]
	global_store_dwordx2 v44, v[232:233], s[36:37] offset:192
	s_mov_b64 exec, -1
	v_mul_f32_e32 v224, v76, v144
	v_mul_f32_e32 v225, v77, v144
	v_mul_f32_e32 v226, v78, v144
	v_mul_f32_e32 v227, v79, v144
	v_fma_f32 v224, v20, v224, v16
	v_fma_f32 v225, v21, v225, v17
	v_fma_f32 v226, v22, v226, v18
	v_fma_f32 v227, v23, v227, v19
	v_sub_f32_e32 v228, v224, v156
	v_sub_f32_e32 v229, v225, v157
	v_sub_f32_e32 v230, v226, v158
	v_sub_f32_e32 v231, v227, v159
	v_add_f32_e32 v220, v220, v228
	v_add_f32_e32 v221, v221, v229
	v_add_f32_e32 v222, v222, v230
	v_add_f32_e32 v223, v223, v231
	v_mov_b32_e32 v156, v224
	v_mov_b32_e32 v157, v225
	v_mov_b32_e32 v158, v226
	v_mov_b32_e32 v159, v227
	v_fma_f32 v228, v220, s55, -v224
	v_fma_f32 v229, v221, s55, -v225
	v_fma_f32 v230, v222, s55, -v226
	v_fma_f32 v231, v223, s55, -v227
	v_cvt_pk_bf16_f32 v56, v228, v229
	v_cvt_pk_bf16_f32 v57, v230, v231
	s_mov_b64 exec, s[38:39]
	global_store_dwordx2 v44, v[56:57], s[36:37] offset:256
	s_mov_b64 exec, -1
	v_mul_f32_e32 v224, v80, v145
	v_mul_f32_e32 v225, v81, v145
	v_mul_f32_e32 v226, v82, v145
	v_mul_f32_e32 v227, v83, v145
	v_fma_f32 v224, v20, v224, v16
	v_fma_f32 v225, v21, v225, v17
	v_fma_f32 v226, v22, v226, v18
	v_fma_f32 v227, v23, v227, v19
	v_sub_f32_e32 v228, v224, v160
	v_sub_f32_e32 v229, v225, v161
	v_sub_f32_e32 v230, v226, v162
	v_sub_f32_e32 v231, v227, v163
	v_add_f32_e32 v220, v220, v228
	v_add_f32_e32 v221, v221, v229
	v_add_f32_e32 v222, v222, v230
	v_add_f32_e32 v223, v223, v231
	v_mov_b32_e32 v160, v224
	v_mov_b32_e32 v161, v225
	v_mov_b32_e32 v162, v226
	v_mov_b32_e32 v163, v227
	v_fma_f32 v228, v220, s55, -v224
	v_fma_f32 v229, v221, s55, -v225
	v_fma_f32 v230, v222, s55, -v226
	v_fma_f32 v231, v223, s55, -v227
	v_cvt_pk_bf16_f32 v232, v228, v229
	v_cvt_pk_bf16_f32 v233, v230, v231
	s_mov_b64 exec, s[38:39]
	global_store_dwordx2 v44, v[232:233], s[36:37] offset:320
	s_mov_b64 exec, -1
	v_mul_f32_e32 v224, v84, v146
	v_mul_f32_e32 v225, v85, v146
	v_mul_f32_e32 v226, v86, v146
	v_mul_f32_e32 v227, v87, v146
	v_fma_f32 v224, v20, v224, v16
	v_fma_f32 v225, v21, v225, v17
	v_fma_f32 v226, v22, v226, v18
	v_fma_f32 v227, v23, v227, v19
	v_sub_f32_e32 v228, v224, v156
	v_sub_f32_e32 v229, v225, v157
	v_sub_f32_e32 v230, v226, v158
	v_sub_f32_e32 v231, v227, v159
	v_add_f32_e32 v220, v220, v228
	v_add_f32_e32 v221, v221, v229
	v_add_f32_e32 v222, v222, v230
	v_add_f32_e32 v223, v223, v231
	v_mov_b32_e32 v156, v224
	v_mov_b32_e32 v157, v225
	v_mov_b32_e32 v158, v226
	v_mov_b32_e32 v159, v227
	v_fma_f32 v228, v220, s55, -v224
	v_fma_f32 v229, v221, s55, -v225
	v_fma_f32 v230, v222, s55, -v226
	v_fma_f32 v231, v223, s55, -v227
	v_cvt_pk_bf16_f32 v56, v228, v229
	v_cvt_pk_bf16_f32 v57, v230, v231
	s_mov_b64 exec, s[38:39]
	global_store_dwordx2 v44, v[56:57], s[36:37] offset:384
	s_mov_b64 exec, -1
	v_mul_f32_e32 v224, v88, v147
	v_mul_f32_e32 v225, v89, v147
	v_mul_f32_e32 v226, v90, v147
	v_mul_f32_e32 v227, v91, v147
	v_fma_f32 v224, v20, v224, v16
	v_fma_f32 v225, v21, v225, v17
	v_fma_f32 v226, v22, v226, v18
	v_fma_f32 v227, v23, v227, v19
	v_sub_f32_e32 v228, v224, v160
	v_sub_f32_e32 v229, v225, v161
	v_sub_f32_e32 v230, v226, v162
	v_sub_f32_e32 v231, v227, v163
	v_add_f32_e32 v220, v220, v228
	v_add_f32_e32 v221, v221, v229
	v_add_f32_e32 v222, v222, v230
	v_add_f32_e32 v223, v223, v231
	v_mov_b32_e32 v160, v224
	v_mov_b32_e32 v161, v225
	v_mov_b32_e32 v162, v226
	v_mov_b32_e32 v163, v227
	v_fma_f32 v228, v220, s55, -v224
	v_fma_f32 v229, v221, s55, -v225
	v_fma_f32 v230, v222, s55, -v226
	v_fma_f32 v231, v223, s55, -v227
	v_cvt_pk_bf16_f32 v232, v228, v229
	v_cvt_pk_bf16_f32 v233, v230, v231
	s_mov_b64 exec, s[38:39]
	global_store_dwordx2 v44, v[232:233], s[36:37] offset:448
	s_mov_b64 exec, -1
	v_mul_f32_e32 v224, v92, v148
	v_mul_f32_e32 v225, v93, v148
	v_mul_f32_e32 v226, v94, v148
; __device__ __forceinline__ unsigned cvt_pk_bf16(float lo, float hi) { unsigned r; asm volatile("v_cvt_pk_bf16_f32 %0, %1, %2" : "=v"(r) : "v"(lo), "v"(hi)); return r; }
; template <int W>
; __device__ __forceinline__ void pool_chunk(const float* x, bf16_t* P, const LAS float* rs  , const f32x4 gs, const f32x4 sh, size_t r0, bool has_halo, int tid) {
;     ...
;         for (int jj = 0; jj < 16; ++jj) { const int i = i0 + jj; constexpr int dummy = 0; (void)dummy;
;             const int slot = (W - 1 + jj) % W;
;             const f32x4 h = xv[jj] * rs[i + 15] * gs + sh;
;             s += h - ring[slot]; ring[slot] = h;
;             const float inv = has_halo ? (1.0f / W) : (1.0f / (float)((i + 1) < W ? (i + 1) : W));
;             const f32x4 o = s * inv - h;
;             u32x2 w; w.x = cvt_pk_bf16(o[0], o[1]); w.y = cvt_pk_bf16(o[2], o[3]);
;             *(u32x2*)(P + img_off((int)(r0 + i), tid * 4, D)) = w; }
	v_mul_f32_e32 v227, v95, v148
	v_fma_f32 v224, v20, v224, v16
	v_fma_f32 v225, v21, v225, v17
	v_fma_f32 v226, v22, v226, v18
	v_fma_f32 v227, v23, v227, v19
	v_sub_f32_e32 v228, v224, v156
	v_sub_f32_e32 v229, v225, v157
	v_sub_f32_e32 v230, v226, v158
	v_sub_f32_e32 v231, v227, v159
	v_add_f32_e32 v220, v220, v228
	v_add_f32_e32 v221, v221, v229
	v_add_f32_e32 v222, v222, v230
	v_add_f32_e32 v223, v223, v231
	v_mov_b32_e32 v156, v224
	v_mov_b32_e32 v157, v225
	v_mov_b32_e32 v158, v226
	v_mov_b32_e32 v159, v227
	v_fma_f32 v228, v220, s55, -v224
	v_fma_f32 v229, v221, s55, -v225
	v_fma_f32 v230, v222, s55, -v226
	v_fma_f32 v231, v223, s55, -v227
	v_cvt_pk_bf16_f32 v56, v228, v229
	v_cvt_pk_bf16_f32 v57, v230, v231
	s_mov_b64 exec, s[38:39]
	global_store_dwordx2 v45, v[56:57], s[36:37] offset:512
	s_mov_b64 exec, -1
	v_mul_f32_e32 v224, v96, v149
	v_mul_f32_e32 v225, v97, v149
	v_mul_f32_e32 v226, v98, v149
	v_mul_f32_e32 v227, v99, v149
	v_fma_f32 v224, v20, v224, v16
	v_fma_f32 v225, v21, v225, v17
	v_fma_f32 v226, v22, v226, v18
	v_fma_f32 v227, v23, v227, v19
	v_sub_f32_e32 v228, v224, v160
	v_sub_f32_e32 v229, v225, v161
	v_sub_f32_e32 v230, v226, v162
	v_sub_f32_e32 v231, v227, v163
	v_add_f32_e32 v220, v220, v228
	v_add_f32_e32 v221, v221, v229
	v_add_f32_e32 v222, v222, v230
	v_add_f32_e32 v223, v223, v231
	v_mov_b32_e32 v160, v224
	v_mov_b32_e32 v161, v225
	v_mov_b32_e32 v162, v226
	v_mov_b32_e32 v163, v227
	v_fma_f32 v228, v220, s55, -v224
	v_fma_f32 v229, v221, s55, -v225
	v_fma_f32 v230, v222, s55, -v226
	v_fma_f32 v231, v223, s55, -v227
	v_cvt_pk_bf16_f32 v232, v228, v229
	v_cvt_pk_bf16_f32 v233, v230, v231
	s_mov_b64 exec, s[38:39]
	global_store_dwordx2 v45, v[232:233], s[36:37] offset:576
	s_mov_b64 exec, -1
	v_mul_f32_e32 v224, v100, v150
	v_mul_f32_e32 v225, v101, v150
	v_mul_f32_e32 v226, v102, v150
	v_mul_f32_e32 v227, v103, v150
	v_fma_f32 v224, v20, v224, v16
	v_fma_f32 v225, v21, v225, v17
	v_fma_f32 v226, v22, v226, v18
	v_fma_f32 v227, v23, v227, v19
	v_sub_f32_e32 v228, v224, v156
	v_sub_f32_e32 v229, v225, v157
	v_sub_f32_e32 v230, v226, v158
	v_sub_f32_e32 v231, v227, v159
	v_add_f32_e32 v220, v220, v228
	v_add_f32_e32 v221, v221, v229
	v_add_f32_e32 v222, v222, v230
	v_add_f32_e32 v223, v223, v231
	v_mov_b32_e32 v156, v224
	v_mov_b32_e32 v157, v225
	v_mov_b32_e32 v158, v226
	v_mov_b32_e32 v159, v227
	v_fma_f32 v228, v220, s55, -v224
	v_fma_f32 v229, v221, s55, -v225
	v_fma_f32 v230, v222, s55, -v226
	v_fma_f32 v231, v223, s55, -v227
	v_cvt_pk_bf16_f32 v56, v228, v229
	v_cvt_pk_bf16_f32 v57, v230, v231
	s_mov_b64 exec, s[38:39]
	global_store_dwordx2 v45, v[56:57], s[36:37] offset:640
	s_mov_b64 exec, -1
	v_mul_f32_e32 v224, v104, v151
	v_mul_f32_e32 v225, v105, v151
	v_mul_f32_e32 v226, v106, v151
	v_mul_f32_e32 v227, v107, v151
	v_fma_f32 v224, v20, v224, v16
	v_fma_f32 v225, v21, v225, v17
	v_fma_f32 v226, v22, v226, v18
	v_fma_f32 v227, v23, v227, v19
	v_sub_f32_e32 v228, v224, v160
	v_sub_f32_e32 v229, v225, v161
	v_sub_f32_e32 v230, v226, v162
	v_sub_f32_e32 v231, v227, v163
	v_add_f32_e32 v220, v220, v228
	v_add_f32_e32 v221, v221, v229
	v_add_f32_e32 v222, v222, v230
	v_add_f32_e32 v223, v223, v231
	v_mov_b32_e32 v160, v224
	v_mov_b32_e32 v161, v225
	v_mov_b32_e32 v162, v226
	v_mov_b32_e32 v163, v227
	v_fma_f32 v228, v220, s55, -v224
	v_fma_f32 v229, v221, s55, -v225
	v_fma_f32 v230, v222, s55, -v226
	v_fma_f32 v231, v223, s55, -v227
	v_cvt_pk_bf16_f32 v232, v228, v229
	v_cvt_pk_bf16_f32 v233, v230, v231
	s_mov_b64 exec, s[38:39]
	global_store_dwordx2 v45, v[232:233], s[36:37] offset:704
	s_mov_b64 exec, -1
	v_mul_f32_e32 v224, v108, v152
	v_mul_f32_e32 v225, v109, v152
	v_mul_f32_e32 v226, v110, v152
	v_mul_f32_e32 v227, v111, v152
	v_fma_f32 v224, v20, v224, v16
	v_fma_f32 v225, v21, v225, v17
; __device__ __forceinline__ unsigned cvt_pk_bf16(float lo, float hi) { unsigned r; asm volatile("v_cvt_pk_bf16_f32 %0, %1, %2" : "=v"(r) : "v"(lo), "v"(hi)); return r; }
; template <int W>
; __device__ __forceinline__ void pool_chunk(const float* x, bf16_t* P, const LAS float* rs  , const f32x4 gs, const f32x4 sh, size_t r0, bool has_halo, int tid) {
;     ...
;     for (int i0 = 0; i0 < 128; i0 += 16) {
;         f32x4 xv[16];
; #pragma unroll
;         for (int jj = 0; jj < 16; ++jj) xv[jj] = *(const f32x4*)(xp + (size_t)(i0 + jj) * D);
; #pragma unroll
;         for (int jj = 0; jj < 16; ++jj) { const int i = i0 + jj; constexpr int dummy = 0; (void)dummy;
;             const int slot = (W - 1 + jj) % W;
;             const f32x4 h = xv[jj] * rs[i + 15] * gs + sh;
;             s += h - ring[slot]; ring[slot] = h;
;             const float inv = has_halo ? (1.0f / W) : (1.0f / (float)((i + 1) < W ? (i + 1) : W));
;             const f32x4 o = s * inv - h;
;             u32x2 w; w.x = cvt_pk_bf16(o[0], o[1]); w.y = cvt_pk_bf16(o[2], o[3]);
;             *(u32x2*)(P + img_off((int)(r0 + i), tid * 4, D)) = w; }
	v_fma_f32 v226, v22, v226, v18
	v_fma_f32 v227, v23, v227, v19
	v_sub_f32_e32 v228, v224, v156
	v_sub_f32_e32 v229, v225, v157
	v_sub_f32_e32 v230, v226, v158
	v_sub_f32_e32 v231, v227, v159
	v_add_f32_e32 v220, v220, v228
	v_add_f32_e32 v221, v221, v229
	v_add_f32_e32 v222, v222, v230
	v_add_f32_e32 v223, v223, v231
	v_mov_b32_e32 v156, v224
	v_mov_b32_e32 v157, v225
	v_mov_b32_e32 v158, v226
	v_mov_b32_e32 v159, v227
	v_fma_f32 v228, v220, s55, -v224
	v_fma_f32 v229, v221, s55, -v225
	v_fma_f32 v230, v222, s55, -v226
	v_fma_f32 v231, v223, s55, -v227
	v_cvt_pk_bf16_f32 v56, v228, v229
	v_cvt_pk_bf16_f32 v57, v230, v231
	s_mov_b64 exec, s[38:39]
	global_store_dwordx2 v45, v[56:57], s[36:37] offset:768
	s_mov_b64 exec, -1
	v_mul_f32_e32 v224, v112, v153
	v_mul_f32_e32 v225, v113, v153
	v_mul_f32_e32 v226, v114, v153
	v_mul_f32_e32 v227, v115, v153
	v_fma_f32 v224, v20, v224, v16
	v_fma_f32 v225, v21, v225, v17
	v_fma_f32 v226, v22, v226, v18
	v_fma_f32 v227, v23, v227, v19
	v_sub_f32_e32 v228, v224, v160
	v_sub_f32_e32 v229, v225, v161
	v_sub_f32_e32 v230, v226, v162
	v_sub_f32_e32 v231, v227, v163
	v_add_f32_e32 v220, v220, v228
	v_add_f32_e32 v221, v221, v229
	v_add_f32_e32 v222, v222, v230
	v_add_f32_e32 v223, v223, v231
	v_mov_b32_e32 v160, v224
	v_mov_b32_e32 v161, v225
	v_mov_b32_e32 v162, v226
	v_mov_b32_e32 v163, v227
	v_fma_f32 v228, v220, s55, -v224
	v_fma_f32 v229, v221, s55, -v225
	v_fma_f32 v230, v222, s55, -v226
	v_fma_f32 v231, v223, s55, -v227
	v_cvt_pk_bf16_f32 v232, v228, v229
	v_cvt_pk_bf16_f32 v233, v230, v231
	s_mov_b64 exec, s[38:39]
	global_store_dwordx2 v45, v[232:233], s[36:37] offset:832
	s_mov_b64 exec, -1
	v_mul_f32_e32 v224, v116, v154
	v_mul_f32_e32 v225, v117, v154
	v_mul_f32_e32 v226, v118, v154
	v_mul_f32_e32 v227, v119, v154
	v_fma_f32 v224, v20, v224, v16
	v_fma_f32 v225, v21, v225, v17
	v_fma_f32 v226, v22, v226, v18
	v_fma_f32 v227, v23, v227, v19
	v_sub_f32_e32 v228, v224, v156
	v_sub_f32_e32 v229, v225, v157
	v_sub_f32_e32 v230, v226, v158
	v_sub_f32_e32 v231, v227, v159
	v_add_f32_e32 v220, v220, v228
	v_add_f32_e32 v221, v221, v229
	v_add_f32_e32 v222, v222, v230
	v_add_f32_e32 v223, v223, v231
	v_mov_b32_e32 v156, v224
	v_mov_b32_e32 v157, v225
	v_mov_b32_e32 v158, v226
	v_mov_b32_e32 v159, v227
	v_fma_f32 v228, v220, s55, -v224
	v_fma_f32 v229, v221, s55, -v225
	v_fma_f32 v230, v222, s55, -v226
	v_fma_f32 v231, v223, s55, -v227
	v_cvt_pk_bf16_f32 v56, v228, v229
	v_cvt_pk_bf16_f32 v57, v230, v231
	s_mov_b64 exec, s[38:39]
	global_store_dwordx2 v45, v[56:57], s[36:37] offset:896
	s_mov_b64 exec, -1
	v_mul_f32_e32 v224, v120, v155
	v_mul_f32_e32 v225, v121, v155
	v_mul_f32_e32 v226, v122, v155
	v_mul_f32_e32 v227, v123, v155
	v_fma_f32 v224, v20, v224, v16
	v_fma_f32 v225, v21, v225, v17
	v_fma_f32 v226, v22, v226, v18
	v_fma_f32 v227, v23, v227, v19
	v_sub_f32_e32 v228, v224, v160
	v_sub_f32_e32 v229, v225, v161
	v_sub_f32_e32 v230, v226, v162
	v_sub_f32_e32 v231, v227, v163
	v_add_f32_e32 v220, v220, v228
	v_add_f32_e32 v221, v221, v229
	v_add_f32_e32 v222, v222, v230
	v_add_f32_e32 v223, v223, v231
	v_mov_b32_e32 v160, v224
	v_mov_b32_e32 v161, v225
	v_mov_b32_e32 v162, v226
	v_mov_b32_e32 v163, v227
	v_fma_f32 v228, v220, s55, -v224
	v_fma_f32 v229, v221, s55, -v225
	v_fma_f32 v230, v222, s55, -v226
	v_fma_f32 v231, v223, s55, -v227
	v_cvt_pk_bf16_f32 v232, v228, v229
	v_cvt_pk_bf16_f32 v233, v230, v231
	s_mov_b64 exec, s[38:39]
	global_store_dwordx2 v45, v[232:233], s[36:37] offset:960
	s_mov_b64 exec, -1
.Lp1_join:
	s_add_u32 s30, s30, 0x20000
	s_addc_u32 s31, s31, 0
	s_cmp_eq_u64 s[38:39], 0
	s_cbranch_scc1 .Lp1_noadv
	s_add_u32 s36, s36, 0x800
	s_addc_u32 s37, s37, 0
.Lp1_noadv:
	s_mov_b64 s[38:39], -1
	s_mov_b32 s41, 0
	s_sub_u32 s40, s40, 1
	s_cmp_lg_u32 s40, 0
	s_cbranch_scc1 .Lp1_group
	s_branch .LBB0_223
